# RETOUT/NAOUT epilogue rewritten: rolling row prefetch of gate (+prev) with counted vmcnt
# speedup vs baseline: 1.0354x; 1.0115x over previous
; __device__ __forceinline__ unsigned cvtpk(float lo, float hi) { f32x2_t v = {lo, hi}; bf16x2_t b = __builtin_convertvector(v, bf16x2_t); return __builtin_bit_cast(unsigned, b); }
; DI void prologue(LAS unsigned char* lds, int G, const int wave_s) {
;     ...
;     const float* x = PIN(lds, 0); bf16_t* XB = (bf16_t*)(ws + OFF_XB); float* rs = (float*)(ws + OFF_RS);
;     for (int row = gw; row < M; row += NGW) {
;         const f32x4* xr = (const f32x4*)(x + (size_t)row * D) + lane;
;         f32x4 v[4]; float ss = 0.f;
; #pragma unroll
;         for (int j = 0; j < 4; ++j) { v[j] = xr[64 * j]; ss += (v[j][0] * v[j][0] + v[j][1] * v[j][1]) + (v[j][2] * v[j][2] + v[j][3] * v[j][3]); }
;         ss = wave_sum(ss);
;         u32x2* o8 = (u32x2*)(XB + (size_t)row * D) + lane;
; #pragma unroll
;         for (int j = 0; j < 4; ++j) { u32x2 w; w.x = cvtpk(v[j][0], v[j][1]); w.y = cvtpk(v[j][2], v[j][3]); o8[64 * j] = w; }
;         if (lane == 0) { rs[row] = ss; rs[M + row] = 0.f; rs[2 * M + row] = 0.f; }
;     }
.LBB0_124:
	s_or_b64 exec, exec, s[10:11]
	v_mov_b32_e32 v1, 0x25f30
	s_cmp_gt_i32 s8, 0xffff
	v_add_u32_e32 v1, 0, v1
	ds_read_b32 v2, v1
	ds_read_b32 v1, v1 offset:4
	s_waitcnt lgkmcnt(0)
	v_readfirstlane_b32 s14, v2
	v_readfirstlane_b32 s15, v1
	s_cbranch_scc1 .LBB0_129
	v_readlane_b32 s9, v254, 47
	s_add_i32 s3, s9, s3
	s_ashr_i32 s9, s8, 31
	s_lshl_b64 s[10:11], s[8:9], 2
	s_lshl_b64 s[18:19], s[8:9], 11
	s_lshl_b64 s[8:9], s[8:9], 12
	s_add_u32 s8, s14, s8
	v_ashrrev_i32_e32 v1, 31, v0
	s_addc_u32 s9, s15, s9
	v_cmp_eq_u32_e64 s[4:5], 0, v0
	v_lshl_add_u64 v[4:5], v[0:1], 3, s[18:19]
	v_lshl_add_u64 v[6:7], v[0:1], 4, s[8:9]
	s_add_u32 s18, s6, 0x3724000
	s_addc_u32 s19, s7, 0
	v_lshl_add_u64 v[4:5], v[4:5], 0, s[18:19]
	s_add_u32 s10, s10, s6
	s_addc_u32 s11, s11, s7
	s_add_u32 s10, s10, 0x3400000
	s_addc_u32 s11, s11, 0
	s_add_u32 s24, s10, 0x40000
	s_addc_u32 s25, s11, 0
	s_add_u32 s26, s10, 0x80000
	s_addc_u32 s27, s11, 0
	s_mov_b64 s[20:21], 0x800000
	s_mov_b64 s[22:23], 0x400000
	v_lshlrev_b32_e32 v60, 2, v0
	v_xor_b32_e32 v61, 4, v60
	v_xor_b32_e32 v62, 8, v60
	v_xor_b32_e32 v63, 16, v60
	v_xor_b32_e32 v64, 32, v60
	v_xor_b32_e32 v65, 64, v60
	v_xor_b32_e32 v66, 0x80, v60
	global_load_dwordx4 v[80:83], v[6:7], off
	global_load_dwordx4 v[84:87], v[6:7], off offset:1024
	global_load_dwordx4 v[88:91], v[6:7], off offset:2048
	global_load_dwordx4 v[92:95], v[6:7], off offset:3072
	v_lshl_add_u64 v[6:7], v[6:7], 0, s[20:21]
	global_load_dwordx4 v[96:99], v[6:7], off
	global_load_dwordx4 v[100:103], v[6:7], off offset:1024
	global_load_dwordx4 v[104:107], v[6:7], off offset:2048
	global_load_dwordx4 v[108:111], v[6:7], off offset:3072
	v_lshl_add_u64 v[6:7], v[6:7], 0, s[20:21]
	s_waitcnt vmcnt(4)
	v_mul_f32_e32 v21, v81, v81
	v_mul_f32_e32 v27, v83, v83
	v_mul_f32_e32 v28, v85, v85
	v_mul_f32_e32 v29, v87, v87
	v_mul_f32_e32 v30, v89, v89
	v_mul_f32_e32 v31, v91, v91
	v_fmac_f32_e32 v21, v80, v80
	v_fmac_f32_e32 v27, v82, v82
	v_fmac_f32_e32 v28, v84, v84
	v_fmac_f32_e32 v29, v86, v86
	v_mul_f32_e32 v32, v93, v93
	v_mul_f32_e32 v33, v95, v95
	v_fmac_f32_e32 v30, v88, v88
	v_fmac_f32_e32 v31, v90, v90
	v_add_f32_e32 v21, v21, v27
	v_add_f32_e32 v27, v28, v29
	v_fmac_f32_e32 v32, v92, v92
	v_fmac_f32_e32 v33, v94, v94
	v_add_f32_e32 v28, v30, v31
	v_add_f32_e32 v21, v21, v27
	v_add_f32_e32 v29, v32, v33
	v_add_f32_e32 v21, v21, v28
	v_add_f32_e32 v27, v21, v29
	ds_bpermute_b32 v28, v61, v27
	v_cvt_pk_bf16_f32 v70, v80, v81
	v_cvt_pk_bf16_f32 v71, v82, v83
	v_cvt_pk_bf16_f32 v72, v84, v85
	v_cvt_pk_bf16_f32 v73, v86, v87
	s_waitcnt lgkmcnt(0)
	v_add_f32_e32 v27, v27, v28
	ds_bpermute_b32 v28, v62, v27
	v_cvt_pk_bf16_f32 v74, v88, v89
	v_cvt_pk_bf16_f32 v75, v90, v91
	v_cvt_pk_bf16_f32 v76, v92, v93
	v_cvt_pk_bf16_f32 v77, v94, v95
	global_store_dwordx2 v[4:5], v[70:71], off
	global_store_dwordx2 v[4:5], v[72:73], off offset:512
	s_waitcnt lgkmcnt(0)
	v_add_f32_e32 v27, v27, v28
	ds_bpermute_b32 v28, v63, v27
	global_store_dwordx2 v[4:5], v[74:75], off offset:1024
	global_store_dwordx2 v[4:5], v[76:77], off offset:1536
	v_lshl_add_u64 v[4:5], v[4:5], 0, s[22:23]
	s_waitcnt lgkmcnt(0)
	v_add_f32_e32 v27, v27, v28
	ds_bpermute_b32 v28, v64, v27
	s_waitcnt lgkmcnt(0)
	v_add_f32_e32 v27, v27, v28
	ds_bpermute_b32 v28, v65, v27
	s_waitcnt lgkmcnt(0)
	v_add_f32_e32 v27, v27, v28
	ds_bpermute_b32 v28, v66, v27
	s_waitcnt lgkmcnt(0)
	v_add_f32_e32 v27, v27, v28
	s_and_saveexec_b64 s[8:9], s[4:5]
	global_store_dword v177, v27, s[10:11]
	global_store_dword v177, v177, s[24:25]
	global_store_dword v177, v177, s[26:27]
	s_or_b64 exec, exec, s[8:9]
	s_add_u32 s10, s10, 0x2000
	s_addc_u32 s11, s11, 0
	s_add_u32 s24, s24, 0x2000
	s_addc_u32 s25, s25, 0
	s_add_u32 s26, s26, 0x2000
	s_addc_u32 s27, s27, 0
	s_mov_b32 s14, 15
; __device__ __forceinline__ unsigned cvtpk(float lo, float hi) { f32x2_t v = {lo, hi}; bf16x2_t b = __builtin_convertvector(v, bf16x2_t); return __builtin_bit_cast(unsigned, b); }
; DI void prologue(LAS unsigned char* lds, int G, const int wave_s) {
;     ...
;     for (int row = gw; row < M; row += NGW) {
;         const f32x4* xr = (const f32x4*)(x + (size_t)row * D) + lane;
;         f32x4 v[4]; float ss = 0.f;
; #pragma unroll
;         for (int j = 0; j < 4; ++j) { v[j] = xr[64 * j]; ss += (v[j][0] * v[j][0] + v[j][1] * v[j][1]) + (v[j][2] * v[j][2] + v[j][3] * v[j][3]); }
;         ss = wave_sum(ss);
;         u32x2* o8 = (u32x2*)(XB + (size_t)row * D) + lane;
; #pragma unroll
;         for (int j = 0; j < 4; ++j) { u32x2 w; w.x = cvtpk(v[j][0], v[j][1]); w.y = cvtpk(v[j][2], v[j][3]); o8[64 * j] = w; }
;         if (lane == 0) { rs[row] = ss; rs[M + row] = 0.f; rs[2 * M + row] = 0.f; }
;     }
.Lrows_top:
	global_load_dwordx4 v[80:83], v[6:7], off
	global_load_dwordx4 v[84:87], v[6:7], off offset:1024
	global_load_dwordx4 v[88:91], v[6:7], off offset:2048
	global_load_dwordx4 v[92:95], v[6:7], off offset:3072
	v_lshl_add_u64 v[6:7], v[6:7], 0, s[20:21]
	s_waitcnt vmcnt(11)
	v_mul_f32_e32 v21, v97, v97
	v_mul_f32_e32 v27, v99, v99
	v_mul_f32_e32 v28, v101, v101
	v_mul_f32_e32 v29, v103, v103
	v_mul_f32_e32 v30, v105, v105
	v_mul_f32_e32 v31, v107, v107
	v_fmac_f32_e32 v21, v96, v96
	v_fmac_f32_e32 v27, v98, v98
	v_fmac_f32_e32 v28, v100, v100
	v_fmac_f32_e32 v29, v102, v102
	v_mul_f32_e32 v32, v109, v109
	v_mul_f32_e32 v33, v111, v111
	v_fmac_f32_e32 v30, v104, v104
	v_fmac_f32_e32 v31, v106, v106
	v_add_f32_e32 v21, v21, v27
	v_add_f32_e32 v27, v28, v29
	v_fmac_f32_e32 v32, v108, v108
	v_fmac_f32_e32 v33, v110, v110
	v_add_f32_e32 v28, v30, v31
	v_add_f32_e32 v21, v21, v27
	v_add_f32_e32 v29, v32, v33
	v_add_f32_e32 v21, v21, v28
	v_add_f32_e32 v27, v21, v29
	ds_bpermute_b32 v28, v61, v27
	v_cvt_pk_bf16_f32 v70, v96, v97
	v_cvt_pk_bf16_f32 v71, v98, v99
	v_cvt_pk_bf16_f32 v72, v100, v101
	v_cvt_pk_bf16_f32 v73, v102, v103
	s_waitcnt lgkmcnt(0)
	v_add_f32_e32 v27, v27, v28
	ds_bpermute_b32 v28, v62, v27
	v_cvt_pk_bf16_f32 v74, v104, v105
	v_cvt_pk_bf16_f32 v75, v106, v107
	v_cvt_pk_bf16_f32 v76, v108, v109
	v_cvt_pk_bf16_f32 v77, v110, v111
	global_store_dwordx2 v[4:5], v[70:71], off
	global_store_dwordx2 v[4:5], v[72:73], off offset:512
	s_waitcnt lgkmcnt(0)
	v_add_f32_e32 v27, v27, v28
	ds_bpermute_b32 v28, v63, v27
	global_store_dwordx2 v[4:5], v[74:75], off offset:1024
	global_store_dwordx2 v[4:5], v[76:77], off offset:1536
	v_lshl_add_u64 v[4:5], v[4:5], 0, s[22:23]
	s_waitcnt lgkmcnt(0)
	v_add_f32_e32 v27, v27, v28
	ds_bpermute_b32 v28, v64, v27
	s_waitcnt lgkmcnt(0)
	v_add_f32_e32 v27, v27, v28
	ds_bpermute_b32 v28, v65, v27
	s_waitcnt lgkmcnt(0)
	v_add_f32_e32 v27, v27, v28
	ds_bpermute_b32 v28, v66, v27
	s_waitcnt lgkmcnt(0)
	v_add_f32_e32 v27, v27, v28
	s_and_saveexec_b64 s[8:9], s[4:5]
	global_store_dword v177, v27, s[10:11]
	global_store_dword v177, v177, s[24:25]
	global_store_dword v177, v177, s[26:27]
	s_or_b64 exec, exec, s[8:9]
	s_add_u32 s10, s10, 0x2000
	s_addc_u32 s11, s11, 0
	s_add_u32 s24, s24, 0x2000
	s_addc_u32 s25, s25, 0
	s_add_u32 s26, s26, 0x2000
	s_addc_u32 s27, s27, 0
	global_load_dwordx4 v[96:99], v[6:7], off
	global_load_dwordx4 v[100:103], v[6:7], off offset:1024
	global_load_dwordx4 v[104:107], v[6:7], off offset:2048
	global_load_dwordx4 v[108:111], v[6:7], off offset:3072
	v_lshl_add_u64 v[6:7], v[6:7], 0, s[20:21]
	s_waitcnt vmcnt(11)
	v_mul_f32_e32 v21, v81, v81
	v_mul_f32_e32 v27, v83, v83
	v_mul_f32_e32 v28, v85, v85
	v_mul_f32_e32 v29, v87, v87
	v_mul_f32_e32 v30, v89, v89
	v_mul_f32_e32 v31, v91, v91
	v_fmac_f32_e32 v21, v80, v80
	v_fmac_f32_e32 v27, v82, v82
	v_fmac_f32_e32 v28, v84, v84
	v_fmac_f32_e32 v29, v86, v86
	v_mul_f32_e32 v32, v93, v93
	v_mul_f32_e32 v33, v95, v95
	v_fmac_f32_e32 v30, v88, v88
	v_fmac_f32_e32 v31, v90, v90
	v_add_f32_e32 v21, v21, v27
	v_add_f32_e32 v27, v28, v29
	v_fmac_f32_e32 v32, v92, v92
	v_fmac_f32_e32 v33, v94, v94
	v_add_f32_e32 v28, v30, v31
	v_add_f32_e32 v21, v21, v27
	v_add_f32_e32 v29, v32, v33
	v_add_f32_e32 v21, v21, v28
	v_add_f32_e32 v27, v21, v29
	ds_bpermute_b32 v28, v61, v27
	v_cvt_pk_bf16_f32 v70, v80, v81
	v_cvt_pk_bf16_f32 v71, v82, v83
	v_cvt_pk_bf16_f32 v72, v84, v85
	v_cvt_pk_bf16_f32 v73, v86, v87
	s_waitcnt lgkmcnt(0)
	v_add_f32_e32 v27, v27, v28
	ds_bpermute_b32 v28, v62, v27
	v_cvt_pk_bf16_f32 v74, v88, v89
	v_cvt_pk_bf16_f32 v75, v90, v91
	v_cvt_pk_bf16_f32 v76, v92, v93
	v_cvt_pk_bf16_f32 v77, v94, v95
	global_store_dwordx2 v[4:5], v[70:71], off
	global_store_dwordx2 v[4:5], v[72:73], off offset:512
	s_waitcnt lgkmcnt(0)
	v_add_f32_e32 v27, v27, v28
	ds_bpermute_b32 v28, v63, v27
	global_store_dwordx2 v[4:5], v[74:75], off offset:1024
	global_store_dwordx2 v[4:5], v[76:77], off offset:1536
	v_lshl_add_u64 v[4:5], v[4:5], 0, s[22:23]
	s_waitcnt lgkmcnt(0)
	v_add_f32_e32 v27, v27, v28
	ds_bpermute_b32 v28, v64, v27
	s_waitcnt lgkmcnt(0)
	v_add_f32_e32 v27, v27, v28
	ds_bpermute_b32 v28, v65, v27
	s_waitcnt lgkmcnt(0)
	v_add_f32_e32 v27, v27, v28
	ds_bpermute_b32 v28, v66, v27
	s_waitcnt lgkmcnt(0)
	v_add_f32_e32 v27, v27, v28
	s_and_saveexec_b64 s[8:9], s[4:5]
	global_store_dword v177, v27, s[10:11]
	global_store_dword v177, v177, s[24:25]
	global_store_dword v177, v177, s[26:27]
	s_or_b64 exec, exec, s[8:9]
	s_add_u32 s10, s10, 0x2000
	s_addc_u32 s11, s11, 0
	s_add_u32 s24, s24, 0x2000
	s_addc_u32 s25, s25, 0
	s_add_u32 s26, s26, 0x2000
	s_addc_u32 s27, s27, 0
	s_sub_i32 s14, s14, 1
	s_cmp_lg_u32 s14, 0
	s_cbranch_scc1 .Lrows_top
	s_waitcnt vmcnt(7)
	v_mul_f32_e32 v21, v97, v97
	v_mul_f32_e32 v27, v99, v99
	v_mul_f32_e32 v28, v101, v101
	v_mul_f32_e32 v29, v103, v103
	v_mul_f32_e32 v30, v105, v105
	v_mul_f32_e32 v31, v107, v107
	v_fmac_f32_e32 v21, v96, v96
	v_fmac_f32_e32 v27, v98, v98
	v_fmac_f32_e32 v28, v100, v100
	v_fmac_f32_e32 v29, v102, v102
	v_mul_f32_e32 v32, v109, v109
	v_mul_f32_e32 v33, v111, v111
	v_fmac_f32_e32 v30, v104, v104
	v_fmac_f32_e32 v31, v106, v106
	v_add_f32_e32 v21, v21, v27
	v_add_f32_e32 v27, v28, v29
	v_fmac_f32_e32 v32, v108, v108
	v_fmac_f32_e32 v33, v110, v110
	v_add_f32_e32 v28, v30, v31
	v_add_f32_e32 v21, v21, v27
	v_add_f32_e32 v29, v32, v33
	v_add_f32_e32 v21, v21, v28
	v_add_f32_e32 v27, v21, v29
	ds_bpermute_b32 v28, v61, v27
	v_cvt_pk_bf16_f32 v70, v96, v97
	v_cvt_pk_bf16_f32 v71, v98, v99
	v_cvt_pk_bf16_f32 v72, v100, v101
	v_cvt_pk_bf16_f32 v73, v102, v103
	s_waitcnt lgkmcnt(0)
	v_add_f32_e32 v27, v27, v28
	ds_bpermute_b32 v28, v62, v27
	v_cvt_pk_bf16_f32 v74, v104, v105
	v_cvt_pk_bf16_f32 v75, v106, v107
	v_cvt_pk_bf16_f32 v76, v108, v109
	v_cvt_pk_bf16_f32 v77, v110, v111
	global_store_dwordx2 v[4:5], v[70:71], off
	global_store_dwordx2 v[4:5], v[72:73], off offset:512
	s_waitcnt lgkmcnt(0)
	v_add_f32_e32 v27, v27, v28
	ds_bpermute_b32 v28, v63, v27
	global_store_dwordx2 v[4:5], v[74:75], off offset:1024
	global_store_dwordx2 v[4:5], v[76:77], off offset:1536
	v_lshl_add_u64 v[4:5], v[4:5], 0, s[22:23]
	s_waitcnt lgkmcnt(0)
	v_add_f32_e32 v27, v27, v28
	ds_bpermute_b32 v28, v64, v27
	s_waitcnt lgkmcnt(0)
	v_add_f32_e32 v27, v27, v28
	ds_bpermute_b32 v28, v65, v27
	s_waitcnt lgkmcnt(0)
	v_add_f32_e32 v27, v27, v28
	ds_bpermute_b32 v28, v66, v27
	s_waitcnt lgkmcnt(0)
	v_add_f32_e32 v27, v27, v28
	s_and_saveexec_b64 s[8:9], s[4:5]
	global_store_dword v177, v27, s[10:11]
	global_store_dword v177, v177, s[24:25]
	global_store_dword v177, v177, s[26:27]
	s_or_b64 exec, exec, s[8:9]
	s_add_u32 s10, s10, 0x2000
	s_addc_u32 s11, s11, 0
	s_add_u32 s24, s24, 0x2000
	s_addc_u32 s25, s25, 0
	s_add_u32 s26, s26, 0x2000
	s_addc_u32 s27, s27, 0

; __device__ __forceinline__ float bf_lo(unsigned w) { return __uint_as_float(w << 16); }
; __device__ __forceinline__ float bf_hi(unsigned w) { return __uint_as_float(w & 0xffff0000u); }
;     __device__ __forceinline__ void operator()(const f32x4 (&acc)[2][2][4][2], const Unit& u, int wr, int wc, int fr, int fq) const {
;     ...
;         } else {
; #pragma unroll
;             for (int ai = 0; ai < 2; ++ai)
; #pragma unroll
;                 for (int m = 0; m < 4; ++m) { const int row = row0 + ai * HALF + m * 16;
;                     bf16_t* rowp = O + (size_t)row * ldc + u.pn * BM + cw; const bf16_t* gp = gate + (size_t)row * ldg + u.pn * BM + cw;
; #pragma unroll
;                     for (int bj = 0; bj < 2; ++bj) { const u32x4 gw = *(const u32x4*)(gp + bj * HALF);
;                         f32x4 v0 = acc[ai][bj][m][0], v1 = acc[ai][bj][m][1];
;                         v0[0] *= bf_lo(gw.x); v0[1] *= bf_hi(gw.x); v0[2] *= bf_lo(gw.y); v0[3] *= bf_hi(gw.y);
;                         v1[0] *= bf_lo(gw.z); v1[1] *= bf_hi(gw.z); v1[2] *= bf_lo(gw.w); v1[3] *= bf_hi(gw.w);
;                         if (mode == M_NAOUT) { const u32x4 pw = *(const u32x4*)(rowp + bj * HALF);
;                             v0[0] += bf_lo(pw.x); v0[1] += bf_hi(pw.x); v0[2] += bf_lo(pw.y); v0[3] += bf_hi(pw.y);
;                             v1[0] += bf_lo(pw.z); v1[1] += bf_hi(pw.z); v1[2] += bf_lo(pw.w); v1[3] += bf_hi(pw.w); }
;                         store8(rowp + bj * HALF, v0, v1); } }
.LBB0_385:
	s_cmp_lt_i32 s37, 3
	s_cbranch_scc1 .LBB0_486
	s_cmp_lg_u32 s37, 3
	s_cbranch_scc0 .LBB0_420
	s_lshl_b32 s6, s40, 8
	s_ashr_i32 s7, s6, 31
	s_lshl_b64 s[38:39], s[6:7], 1
	v_lshlrev_b64 v[128:129], 1, v[148:149]
	s_and_b64 vcc, exec, s[74:75]
	s_cbranch_vccnz .Lgate_naout
	v_mov_b32_e32 v138, v164
	v_mov_b64_e32 v[132:133], s[78:79]
	v_mad_i64_i32 v[132:133], s[98:99], v138, s50, v[132:133]
	v_lshl_add_u64 v[132:133], v[132:133], 0, s[38:39]
	v_lshl_add_u64 v[132:133], v[132:133], 0, v[128:129]
	global_load_dwordx4 v[182:185], v[132:133], off
	global_load_dwordx4 v[186:189], v[132:133], off offset:256
	v_add_u32_e32 v138, 0x10, v164
	v_mov_b64_e32 v[132:133], s[78:79]
	v_mad_i64_i32 v[132:133], s[98:99], v138, s50, v[132:133]
	v_lshl_add_u64 v[132:133], v[132:133], 0, s[38:39]
	v_lshl_add_u64 v[132:133], v[132:133], 0, v[128:129]
	global_load_dwordx4 v[190:193], v[132:133], off
	global_load_dwordx4 v[194:197], v[132:133], off offset:256
	v_add_u32_e32 v138, 0x20, v164
	v_mov_b64_e32 v[132:133], s[78:79]
	v_mad_i64_i32 v[132:133], s[98:99], v138, s50, v[132:133]
	v_lshl_add_u64 v[132:133], v[132:133], 0, s[38:39]
	v_lshl_add_u64 v[132:133], v[132:133], 0, v[128:129]
	global_load_dwordx4 v[198:201], v[132:133], off
	global_load_dwordx4 v[202:205], v[132:133], off offset:256
	v_add_u32_e32 v138, 0x30, v164
	v_mov_b64_e32 v[132:133], s[78:79]
	v_mad_i64_i32 v[132:133], s[98:99], v138, s50, v[132:133]
	v_lshl_add_u64 v[132:133], v[132:133], 0, s[38:39]
	v_lshl_add_u64 v[132:133], v[132:133], 0, v[128:129]
	global_load_dwordx4 v[206:209], v[132:133], off
	global_load_dwordx4 v[212:215], v[132:133], off offset:256
	v_add_u32_e32 v138, 0x80, v164
	v_mov_b64_e32 v[132:133], s[78:79]
	v_mad_i64_i32 v[132:133], s[98:99], v138, s50, v[132:133]
	v_lshl_add_u64 v[132:133], v[132:133], 0, s[38:39]
	v_lshl_add_u64 v[132:133], v[132:133], 0, v[128:129]
	global_load_dwordx4 v[216:219], v[132:133], off
	global_load_dwordx4 v[220:223], v[132:133], off offset:256
	v_add_u32_e32 v138, 0x90, v164
	v_mov_b64_e32 v[132:133], s[78:79]
	v_mad_i64_i32 v[132:133], s[98:99], v138, s50, v[132:133]
	v_lshl_add_u64 v[132:133], v[132:133], 0, s[38:39]
	v_lshl_add_u64 v[132:133], v[132:133], 0, v[128:129]
	global_load_dwordx4 v[224:227], v[132:133], off
	global_load_dwordx4 v[228:231], v[132:133], off offset:256
	s_waitcnt vmcnt(10)
	v_mov_b32_e32 v138, v164
	v_mad_i64_i32 v[130:131], s[98:99], s82, v138, 0
	v_lshl_add_u64 v[130:131], v[130:131], 1, s[84:85]
	v_lshl_add_u64 v[130:131], v[130:131], 0, s[38:39]
	v_lshl_add_u64 v[130:131], v[130:131], 0, v[128:129]
	v_lshlrev_b32_e32 v166, 16, v182
	v_and_b32_e32 v167, 0xffff0000, v182
	v_lshlrev_b32_e32 v168, 16, v183
	v_and_b32_e32 v169, 0xffff0000, v183
	v_lshlrev_b32_e32 v170, 16, v184
	v_and_b32_e32 v171, 0xffff0000, v184
	v_lshlrev_b32_e32 v172, 16, v185
	v_and_b32_e32 v173, 0xffff0000, v185
	v_pk_mul_f32 v[166:167], v[124:125], v[166:167]
	v_pk_mul_f32 v[168:169], v[126:127], v[168:169]
	v_pk_mul_f32 v[170:171], v[120:121], v[170:171]
	v_pk_mul_f32 v[172:173], v[122:123], v[172:173]
	v_cvt_pk_bf16_f32 v134, v166, v167
	v_cvt_pk_bf16_f32 v135, v168, v169
	v_cvt_pk_bf16_f32 v136, v170, v171
	v_cvt_pk_bf16_f32 v137, v172, v173
	global_store_dwordx4 v[130:131], v[134:137], off
	v_lshlrev_b32_e32 v166, 16, v186
	v_and_b32_e32 v167, 0xffff0000, v186
	v_lshlrev_b32_e32 v168, 16, v187
	v_and_b32_e32 v169, 0xffff0000, v187
	v_lshlrev_b32_e32 v170, 16, v188
	v_and_b32_e32 v171, 0xffff0000, v188
	v_lshlrev_b32_e32 v172, 16, v189
	v_and_b32_e32 v173, 0xffff0000, v189
	v_pk_mul_f32 v[166:167], v[108:109], v[166:167]
	v_pk_mul_f32 v[168:169], v[110:111], v[168:169]
	v_pk_mul_f32 v[170:171], v[104:105], v[170:171]
	v_pk_mul_f32 v[172:173], v[106:107], v[172:173]
	v_cvt_pk_bf16_f32 v232, v166, v167
	v_cvt_pk_bf16_f32 v233, v168, v169
	v_cvt_pk_bf16_f32 v234, v170, v171
	v_cvt_pk_bf16_f32 v235, v172, v173
	global_store_dwordx4 v[130:131], v[232:235], off offset:256
	v_add_u32_e32 v138, 0xa0, v164
	v_mov_b64_e32 v[132:133], s[78:79]
	v_mad_i64_i32 v[132:133], s[98:99], v138, s50, v[132:133]
	v_lshl_add_u64 v[132:133], v[132:133], 0, s[38:39]
	v_lshl_add_u64 v[132:133], v[132:133], 0, v[128:129]
	global_load_dwordx4 v[182:185], v[132:133], off
	global_load_dwordx4 v[186:189], v[132:133], off offset:256
	s_waitcnt vmcnt(12)
	v_add_u32_e32 v138, 0x10, v164
	v_mad_i64_i32 v[130:131], s[98:99], s82, v138, 0
	v_lshl_add_u64 v[130:131], v[130:131], 1, s[84:85]
	v_lshl_add_u64 v[130:131], v[130:131], 0, s[38:39]
	v_lshl_add_u64 v[130:131], v[130:131], 0, v[128:129]
	v_lshlrev_b32_e32 v166, 16, v190
	v_and_b32_e32 v167, 0xffff0000, v190
	v_lshlrev_b32_e32 v168, 16, v191
	v_and_b32_e32 v169, 0xffff0000, v191
	v_lshlrev_b32_e32 v170, 16, v192
	v_and_b32_e32 v171, 0xffff0000, v192
	v_lshlrev_b32_e32 v172, 16, v193
	v_and_b32_e32 v173, 0xffff0000, v193
	v_pk_mul_f32 v[166:167], v[116:117], v[166:167]
	v_pk_mul_f32 v[168:169], v[118:119], v[168:169]
	v_pk_mul_f32 v[170:171], v[112:113], v[170:171]
	v_pk_mul_f32 v[172:173], v[114:115], v[172:173]
	v_cvt_pk_bf16_f32 v134, v166, v167
	v_cvt_pk_bf16_f32 v135, v168, v169
	v_cvt_pk_bf16_f32 v136, v170, v171
	v_cvt_pk_bf16_f32 v137, v172, v173
	global_store_dwordx4 v[130:131], v[134:137], off
	v_lshlrev_b32_e32 v166, 16, v194
	v_and_b32_e32 v167, 0xffff0000, v194
	v_lshlrev_b32_e32 v168, 16, v195
	v_and_b32_e32 v169, 0xffff0000, v195
	v_lshlrev_b32_e32 v170, 16, v196
	v_and_b32_e32 v171, 0xffff0000, v196
	v_lshlrev_b32_e32 v172, 16, v197
	v_and_b32_e32 v173, 0xffff0000, v197
	v_pk_mul_f32 v[166:167], v[92:93], v[166:167]
	v_pk_mul_f32 v[168:169], v[94:95], v[168:169]
	v_pk_mul_f32 v[170:171], v[88:89], v[170:171]
	v_pk_mul_f32 v[172:173], v[90:91], v[172:173]
	v_cvt_pk_bf16_f32 v232, v166, v167
	v_cvt_pk_bf16_f32 v233, v168, v169
	v_cvt_pk_bf16_f32 v234, v170, v171
	v_cvt_pk_bf16_f32 v235, v172, v173
	global_store_dwordx4 v[130:131], v[232:235], off offset:256
	v_add_u32_e32 v138, 0xb0, v164
	v_mov_b64_e32 v[132:133], s[78:79]
	v_mad_i64_i32 v[132:133], s[98:99], v138, s50, v[132:133]
	v_lshl_add_u64 v[132:133], v[132:133], 0, s[38:39]
	v_lshl_add_u64 v[132:133], v[132:133], 0, v[128:129]
	global_load_dwordx4 v[190:193], v[132:133], off
	global_load_dwordx4 v[194:197], v[132:133], off offset:256
	s_waitcnt vmcnt(14)
; __device__ __forceinline__ float bf_lo(unsigned w) { return __uint_as_float(w << 16); }
; __device__ __forceinline__ float bf_hi(unsigned w) { return __uint_as_float(w & 0xffff0000u); }
;     __device__ __forceinline__ void operator()(const f32x4 (&acc)[2][2][4][2], const Unit& u, int wr, int wc, int fr, int fq) const {
;     ...
;         } else {
; #pragma unroll
;             for (int ai = 0; ai < 2; ++ai)
; #pragma unroll
;                 for (int m = 0; m < 4; ++m) { const int row = row0 + ai * HALF + m * 16;
;                     bf16_t* rowp = O + (size_t)row * ldc + u.pn * BM + cw; const bf16_t* gp = gate + (size_t)row * ldg + u.pn * BM + cw;
; #pragma unroll
;                     for (int bj = 0; bj < 2; ++bj) { const u32x4 gw = *(const u32x4*)(gp + bj * HALF);
;                         f32x4 v0 = acc[ai][bj][m][0], v1 = acc[ai][bj][m][1];
;                         v0[0] *= bf_lo(gw.x); v0[1] *= bf_hi(gw.x); v0[2] *= bf_lo(gw.y); v0[3] *= bf_hi(gw.y);
;                         v1[0] *= bf_lo(gw.z); v1[1] *= bf_hi(gw.z); v1[2] *= bf_lo(gw.w); v1[3] *= bf_hi(gw.w);
;                         if (mode == M_NAOUT) { const u32x4 pw = *(const u32x4*)(rowp + bj * HALF);
;                             v0[0] += bf_lo(pw.x); v0[1] += bf_hi(pw.x); v0[2] += bf_lo(pw.y); v0[3] += bf_hi(pw.y);
;                             v1[0] += bf_lo(pw.z); v1[1] += bf_hi(pw.z); v1[2] += bf_lo(pw.w); v1[3] += bf_hi(pw.w); }
;                         store8(rowp + bj * HALF, v0, v1); } }
	v_add_u32_e32 v138, 0x20, v164
	v_mad_i64_i32 v[130:131], s[98:99], s82, v138, 0
	v_lshl_add_u64 v[130:131], v[130:131], 1, s[84:85]
	v_lshl_add_u64 v[130:131], v[130:131], 0, s[38:39]
	v_lshl_add_u64 v[130:131], v[130:131], 0, v[128:129]
	v_lshlrev_b32_e32 v166, 16, v198
	v_and_b32_e32 v167, 0xffff0000, v198
	v_lshlrev_b32_e32 v168, 16, v199
	v_and_b32_e32 v169, 0xffff0000, v199
	v_lshlrev_b32_e32 v170, 16, v200
	v_and_b32_e32 v171, 0xffff0000, v200
	v_lshlrev_b32_e32 v172, 16, v201
	v_and_b32_e32 v173, 0xffff0000, v201
	v_pk_mul_f32 v[166:167], v[100:101], v[166:167]
	v_pk_mul_f32 v[168:169], v[102:103], v[168:169]
	v_pk_mul_f32 v[170:171], v[96:97], v[170:171]
	v_pk_mul_f32 v[172:173], v[98:99], v[172:173]
	v_cvt_pk_bf16_f32 v134, v166, v167
	v_cvt_pk_bf16_f32 v135, v168, v169
	v_cvt_pk_bf16_f32 v136, v170, v171
	v_cvt_pk_bf16_f32 v137, v172, v173
	global_store_dwordx4 v[130:131], v[134:137], off
	v_lshlrev_b32_e32 v166, 16, v202
	v_and_b32_e32 v167, 0xffff0000, v202
	v_lshlrev_b32_e32 v168, 16, v203
	v_and_b32_e32 v169, 0xffff0000, v203
	v_lshlrev_b32_e32 v170, 16, v204
	v_and_b32_e32 v171, 0xffff0000, v204
	v_lshlrev_b32_e32 v172, 16, v205
	v_and_b32_e32 v173, 0xffff0000, v205
	v_pk_mul_f32 v[166:167], v[76:77], v[166:167]
	v_pk_mul_f32 v[168:169], v[78:79], v[168:169]
	v_pk_mul_f32 v[170:171], v[72:73], v[170:171]
	v_pk_mul_f32 v[172:173], v[74:75], v[172:173]
	v_cvt_pk_bf16_f32 v232, v166, v167
	v_cvt_pk_bf16_f32 v233, v168, v169
	v_cvt_pk_bf16_f32 v234, v170, v171
	v_cvt_pk_bf16_f32 v235, v172, v173
	global_store_dwordx4 v[130:131], v[232:235], off offset:256
	s_waitcnt vmcnt(14)
	v_add_u32_e32 v138, 0x30, v164
	v_mad_i64_i32 v[130:131], s[98:99], s82, v138, 0
	v_lshl_add_u64 v[130:131], v[130:131], 1, s[84:85]
	v_lshl_add_u64 v[130:131], v[130:131], 0, s[38:39]
	v_lshl_add_u64 v[130:131], v[130:131], 0, v[128:129]
	v_lshlrev_b32_e32 v166, 16, v206
	v_and_b32_e32 v167, 0xffff0000, v206
	v_lshlrev_b32_e32 v168, 16, v207
	v_and_b32_e32 v169, 0xffff0000, v207
	v_lshlrev_b32_e32 v170, 16, v208
	v_and_b32_e32 v171, 0xffff0000, v208
	v_lshlrev_b32_e32 v172, 16, v209
	v_and_b32_e32 v173, 0xffff0000, v209
	v_pk_mul_f32 v[166:167], v[84:85], v[166:167]
	v_pk_mul_f32 v[168:169], v[86:87], v[168:169]
	v_pk_mul_f32 v[170:171], v[80:81], v[170:171]
	v_pk_mul_f32 v[172:173], v[82:83], v[172:173]
	v_cvt_pk_bf16_f32 v134, v166, v167
	v_cvt_pk_bf16_f32 v135, v168, v169
	v_cvt_pk_bf16_f32 v136, v170, v171
	v_cvt_pk_bf16_f32 v137, v172, v173
	global_store_dwordx4 v[130:131], v[134:137], off
	v_lshlrev_b32_e32 v166, 16, v212
	v_and_b32_e32 v167, 0xffff0000, v212
	v_lshlrev_b32_e32 v168, 16, v213
	v_and_b32_e32 v169, 0xffff0000, v213
	v_lshlrev_b32_e32 v170, 16, v214
	v_and_b32_e32 v171, 0xffff0000, v214
	v_lshlrev_b32_e32 v172, 16, v215
	v_and_b32_e32 v173, 0xffff0000, v215
	v_pk_mul_f32 v[166:167], v[68:69], v[166:167]
	v_pk_mul_f32 v[168:169], v[70:71], v[168:169]
	v_pk_mul_f32 v[170:171], v[64:65], v[170:171]
	v_pk_mul_f32 v[172:173], v[66:67], v[172:173]
	v_cvt_pk_bf16_f32 v232, v166, v167
	v_cvt_pk_bf16_f32 v233, v168, v169
	v_cvt_pk_bf16_f32 v234, v170, v171
	v_cvt_pk_bf16_f32 v235, v172, v173
	global_store_dwordx4 v[130:131], v[232:235], off offset:256
	s_waitcnt vmcnt(14)
	v_add_u32_e32 v138, 0x80, v164
	v_mad_i64_i32 v[130:131], s[98:99], s82, v138, 0
	v_lshl_add_u64 v[130:131], v[130:131], 1, s[84:85]
	v_lshl_add_u64 v[130:131], v[130:131], 0, s[38:39]
	v_lshl_add_u64 v[130:131], v[130:131], 0, v[128:129]
	v_lshlrev_b32_e32 v166, 16, v216
	v_and_b32_e32 v167, 0xffff0000, v216
	v_lshlrev_b32_e32 v168, 16, v217
	v_and_b32_e32 v169, 0xffff0000, v217
	v_lshlrev_b32_e32 v170, 16, v218
	v_and_b32_e32 v171, 0xffff0000, v218
	v_lshlrev_b32_e32 v172, 16, v219
	v_and_b32_e32 v173, 0xffff0000, v219
	v_pk_mul_f32 v[166:167], v[60:61], v[166:167]
	v_pk_mul_f32 v[168:169], v[62:63], v[168:169]
	v_pk_mul_f32 v[170:171], v[56:57], v[170:171]
	v_pk_mul_f32 v[172:173], v[58:59], v[172:173]
	v_cvt_pk_bf16_f32 v134, v166, v167
	v_cvt_pk_bf16_f32 v135, v168, v169
	v_cvt_pk_bf16_f32 v136, v170, v171
	v_cvt_pk_bf16_f32 v137, v172, v173
	global_store_dwordx4 v[130:131], v[134:137], off
	v_lshlrev_b32_e32 v166, 16, v220
	v_and_b32_e32 v167, 0xffff0000, v220
	v_lshlrev_b32_e32 v168, 16, v221
	v_and_b32_e32 v169, 0xffff0000, v221
	v_lshlrev_b32_e32 v170, 16, v222
	v_and_b32_e32 v171, 0xffff0000, v222
	v_lshlrev_b32_e32 v172, 16, v223
	v_and_b32_e32 v173, 0xffff0000, v223
	v_pk_mul_f32 v[166:167], v[44:45], v[166:167]
	v_pk_mul_f32 v[168:169], v[46:47], v[168:169]
	v_pk_mul_f32 v[170:171], v[40:41], v[170:171]
	v_pk_mul_f32 v[172:173], v[42:43], v[172:173]
	v_cvt_pk_bf16_f32 v232, v166, v167
	v_cvt_pk_bf16_f32 v233, v168, v169
	v_cvt_pk_bf16_f32 v234, v170, v171
	v_cvt_pk_bf16_f32 v235, v172, v173
	global_store_dwordx4 v[130:131], v[232:235], off offset:256
	s_waitcnt vmcnt(14)
; __device__ __forceinline__ float bf_lo(unsigned w) { return __uint_as_float(w << 16); }
; __device__ __forceinline__ float bf_hi(unsigned w) { return __uint_as_float(w & 0xffff0000u); }
;     __device__ __forceinline__ void operator()(const f32x4 (&acc)[2][2][4][2], const Unit& u, int wr, int wc, int fr, int fq) const {
;     ...
;         } else {
; #pragma unroll
;             for (int ai = 0; ai < 2; ++ai)
; #pragma unroll
;                 for (int m = 0; m < 4; ++m) { const int row = row0 + ai * HALF + m * 16;
;                     bf16_t* rowp = O + (size_t)row * ldc + u.pn * BM + cw; const bf16_t* gp = gate + (size_t)row * ldg + u.pn * BM + cw;
; #pragma unroll
;                     for (int bj = 0; bj < 2; ++bj) { const u32x4 gw = *(const u32x4*)(gp + bj * HALF);
;                         f32x4 v0 = acc[ai][bj][m][0], v1 = acc[ai][bj][m][1];
;                         v0[0] *= bf_lo(gw.x); v0[1] *= bf_hi(gw.x); v0[2] *= bf_lo(gw.y); v0[3] *= bf_hi(gw.y);
;                         v1[0] *= bf_lo(gw.z); v1[1] *= bf_hi(gw.z); v1[2] *= bf_lo(gw.w); v1[3] *= bf_hi(gw.w);
;                         if (mode == M_NAOUT) { const u32x4 pw = *(const u32x4*)(rowp + bj * HALF);
;                             v0[0] += bf_lo(pw.x); v0[1] += bf_hi(pw.x); v0[2] += bf_lo(pw.y); v0[3] += bf_hi(pw.y);
;                             v1[0] += bf_lo(pw.z); v1[1] += bf_hi(pw.z); v1[2] += bf_lo(pw.w); v1[3] += bf_hi(pw.w); }
;                         store8(rowp + bj * HALF, v0, v1); } }
	v_add_u32_e32 v138, 0x90, v164
	v_mad_i64_i32 v[130:131], s[98:99], s82, v138, 0
	v_lshl_add_u64 v[130:131], v[130:131], 1, s[84:85]
	v_lshl_add_u64 v[130:131], v[130:131], 0, s[38:39]
	v_lshl_add_u64 v[130:131], v[130:131], 0, v[128:129]
	v_lshlrev_b32_e32 v166, 16, v224
	v_and_b32_e32 v167, 0xffff0000, v224
	v_lshlrev_b32_e32 v168, 16, v225
	v_and_b32_e32 v169, 0xffff0000, v225
	v_lshlrev_b32_e32 v170, 16, v226
	v_and_b32_e32 v171, 0xffff0000, v226
	v_lshlrev_b32_e32 v172, 16, v227
	v_and_b32_e32 v173, 0xffff0000, v227
	v_pk_mul_f32 v[166:167], v[52:53], v[166:167]
	v_pk_mul_f32 v[168:169], v[54:55], v[168:169]
	v_pk_mul_f32 v[170:171], v[48:49], v[170:171]
	v_pk_mul_f32 v[172:173], v[50:51], v[172:173]
	v_cvt_pk_bf16_f32 v134, v166, v167
	v_cvt_pk_bf16_f32 v135, v168, v169
	v_cvt_pk_bf16_f32 v136, v170, v171
	v_cvt_pk_bf16_f32 v137, v172, v173
	global_store_dwordx4 v[130:131], v[134:137], off
	v_lshlrev_b32_e32 v166, 16, v228
	v_and_b32_e32 v167, 0xffff0000, v228
	v_lshlrev_b32_e32 v168, 16, v229
	v_and_b32_e32 v169, 0xffff0000, v229
	v_lshlrev_b32_e32 v170, 16, v230
	v_and_b32_e32 v171, 0xffff0000, v230
	v_lshlrev_b32_e32 v172, 16, v231
	v_and_b32_e32 v173, 0xffff0000, v231
	v_pk_mul_f32 v[166:167], v[28:29], v[166:167]
	v_pk_mul_f32 v[168:169], v[30:31], v[168:169]
	v_pk_mul_f32 v[170:171], v[24:25], v[170:171]
	v_pk_mul_f32 v[172:173], v[26:27], v[172:173]
	v_cvt_pk_bf16_f32 v232, v166, v167
	v_cvt_pk_bf16_f32 v233, v168, v169
	v_cvt_pk_bf16_f32 v234, v170, v171
	v_cvt_pk_bf16_f32 v235, v172, v173
	global_store_dwordx4 v[130:131], v[232:235], off offset:256
	s_waitcnt vmcnt(12)
	v_add_u32_e32 v138, 0xa0, v164
	v_mad_i64_i32 v[130:131], s[98:99], s82, v138, 0
	v_lshl_add_u64 v[130:131], v[130:131], 1, s[84:85]
	v_lshl_add_u64 v[130:131], v[130:131], 0, s[38:39]
	v_lshl_add_u64 v[130:131], v[130:131], 0, v[128:129]
	v_lshlrev_b32_e32 v166, 16, v182
	v_and_b32_e32 v167, 0xffff0000, v182
	v_lshlrev_b32_e32 v168, 16, v183
	v_and_b32_e32 v169, 0xffff0000, v183
	v_lshlrev_b32_e32 v170, 16, v184
	v_and_b32_e32 v171, 0xffff0000, v184
	v_lshlrev_b32_e32 v172, 16, v185
	v_and_b32_e32 v173, 0xffff0000, v185
	v_pk_mul_f32 v[166:167], v[36:37], v[166:167]
	v_pk_mul_f32 v[168:169], v[38:39], v[168:169]
	v_pk_mul_f32 v[170:171], v[32:33], v[170:171]
	v_pk_mul_f32 v[172:173], v[34:35], v[172:173]
	v_cvt_pk_bf16_f32 v134, v166, v167
	v_cvt_pk_bf16_f32 v135, v168, v169
	v_cvt_pk_bf16_f32 v136, v170, v171
	v_cvt_pk_bf16_f32 v137, v172, v173
	global_store_dwordx4 v[130:131], v[134:137], off
	v_lshlrev_b32_e32 v166, 16, v186
	v_and_b32_e32 v167, 0xffff0000, v186
	v_lshlrev_b32_e32 v168, 16, v187
	v_and_b32_e32 v169, 0xffff0000, v187
	v_lshlrev_b32_e32 v170, 16, v188
	v_and_b32_e32 v171, 0xffff0000, v188
	v_lshlrev_b32_e32 v172, 16, v189
	v_and_b32_e32 v173, 0xffff0000, v189
	v_pk_mul_f32 v[166:167], v[12:13], v[166:167]
	v_pk_mul_f32 v[168:169], v[14:15], v[168:169]
	v_pk_mul_f32 v[170:171], v[8:9], v[170:171]
	v_pk_mul_f32 v[172:173], v[10:11], v[172:173]
	v_cvt_pk_bf16_f32 v232, v166, v167
	v_cvt_pk_bf16_f32 v233, v168, v169
	v_cvt_pk_bf16_f32 v234, v170, v171
	v_cvt_pk_bf16_f32 v235, v172, v173
	global_store_dwordx4 v[130:131], v[232:235], off offset:256
	s_waitcnt vmcnt(10)
	v_add_u32_e32 v138, 0xb0, v164
	v_mad_i64_i32 v[130:131], s[98:99], s82, v138, 0
	v_lshl_add_u64 v[130:131], v[130:131], 1, s[84:85]
	v_lshl_add_u64 v[130:131], v[130:131], 0, s[38:39]
	v_lshl_add_u64 v[130:131], v[130:131], 0, v[128:129]
	v_lshlrev_b32_e32 v166, 16, v190
	v_and_b32_e32 v167, 0xffff0000, v190
	v_lshlrev_b32_e32 v168, 16, v191
	v_and_b32_e32 v169, 0xffff0000, v191
	v_lshlrev_b32_e32 v170, 16, v192
	v_and_b32_e32 v171, 0xffff0000, v192
	v_lshlrev_b32_e32 v172, 16, v193
	v_and_b32_e32 v173, 0xffff0000, v193
	v_pk_mul_f32 v[166:167], v[20:21], v[166:167]
	v_pk_mul_f32 v[168:169], v[22:23], v[168:169]
	v_pk_mul_f32 v[170:171], v[16:17], v[170:171]
	v_pk_mul_f32 v[172:173], v[18:19], v[172:173]
	v_cvt_pk_bf16_f32 v134, v166, v167
	v_cvt_pk_bf16_f32 v135, v168, v169
	v_cvt_pk_bf16_f32 v136, v170, v171
	v_cvt_pk_bf16_f32 v137, v172, v173
	global_store_dwordx4 v[130:131], v[134:137], off
	v_lshlrev_b32_e32 v166, 16, v194
	v_and_b32_e32 v167, 0xffff0000, v194
	v_lshlrev_b32_e32 v168, 16, v195
	v_and_b32_e32 v169, 0xffff0000, v195
	v_lshlrev_b32_e32 v170, 16, v196
	v_and_b32_e32 v171, 0xffff0000, v196
	v_lshlrev_b32_e32 v172, 16, v197
	v_and_b32_e32 v173, 0xffff0000, v197
	v_pk_mul_f32 v[166:167], v[4:5], v[166:167]
	v_pk_mul_f32 v[168:169], v[6:7], v[168:169]
	v_pk_mul_f32 v[170:171], v[0:1], v[170:171]
	v_pk_mul_f32 v[172:173], v[2:3], v[172:173]
	v_cvt_pk_bf16_f32 v232, v166, v167
	v_cvt_pk_bf16_f32 v233, v168, v169
	v_cvt_pk_bf16_f32 v234, v170, v171
	v_cvt_pk_bf16_f32 v235, v172, v173
	global_store_dwordx4 v[130:131], v[232:235], off offset:256
	s_branch .Lgate_done
; __device__ __forceinline__ float bf_lo(unsigned w) { return __uint_as_float(w << 16); }
; __device__ __forceinline__ float bf_hi(unsigned w) { return __uint_as_float(w & 0xffff0000u); }
;     __device__ __forceinline__ void operator()(const f32x4 (&acc)[2][2][4][2], const Unit& u, int wr, int wc, int fr, int fq) const {
;     ...
;         } else {
; #pragma unroll
;             for (int ai = 0; ai < 2; ++ai)
; #pragma unroll
;                 for (int m = 0; m < 4; ++m) { const int row = row0 + ai * HALF + m * 16;
;                     bf16_t* rowp = O + (size_t)row * ldc + u.pn * BM + cw; const bf16_t* gp = gate + (size_t)row * ldg + u.pn * BM + cw;
; #pragma unroll
;                     for (int bj = 0; bj < 2; ++bj) { const u32x4 gw = *(const u32x4*)(gp + bj * HALF);
;                         f32x4 v0 = acc[ai][bj][m][0], v1 = acc[ai][bj][m][1];
;                         v0[0] *= bf_lo(gw.x); v0[1] *= bf_hi(gw.x); v0[2] *= bf_lo(gw.y); v0[3] *= bf_hi(gw.y);
;                         v1[0] *= bf_lo(gw.z); v1[1] *= bf_hi(gw.z); v1[2] *= bf_lo(gw.w); v1[3] *= bf_hi(gw.w);
;                         if (mode == M_NAOUT) { const u32x4 pw = *(const u32x4*)(rowp + bj * HALF);
;                             v0[0] += bf_lo(pw.x); v0[1] += bf_hi(pw.x); v0[2] += bf_lo(pw.y); v0[3] += bf_hi(pw.y);
;                             v1[0] += bf_lo(pw.z); v1[1] += bf_hi(pw.z); v1[2] += bf_lo(pw.w); v1[3] += bf_hi(pw.w); }
;                         store8(rowp + bj * HALF, v0, v1); } }
.Lgate_naout:
	v_mov_b32_e32 v138, v164
	v_mov_b64_e32 v[132:133], s[78:79]
	v_mad_i64_i32 v[132:133], s[98:99], v138, s50, v[132:133]
	v_lshl_add_u64 v[132:133], v[132:133], 0, s[38:39]
	v_lshl_add_u64 v[132:133], v[132:133], 0, v[128:129]
	global_load_dwordx4 v[182:185], v[132:133], off
	global_load_dwordx4 v[186:189], v[132:133], off offset:256
	v_mad_i64_i32 v[130:131], s[98:99], s82, v138, 0
	v_lshl_add_u64 v[130:131], v[130:131], 1, s[84:85]
	v_lshl_add_u64 v[130:131], v[130:131], 0, s[38:39]
	v_lshl_add_u64 v[130:131], v[130:131], 0, v[128:129]
	global_load_dwordx4 v[190:193], v[130:131], off
	global_load_dwordx4 v[194:197], v[130:131], off offset:256
	v_add_u32_e32 v138, 0x10, v164
	v_mov_b64_e32 v[132:133], s[78:79]
	v_mad_i64_i32 v[132:133], s[98:99], v138, s50, v[132:133]
	v_lshl_add_u64 v[132:133], v[132:133], 0, s[38:39]
	v_lshl_add_u64 v[132:133], v[132:133], 0, v[128:129]
	global_load_dwordx4 v[198:201], v[132:133], off
	global_load_dwordx4 v[202:205], v[132:133], off offset:256
	v_mad_i64_i32 v[130:131], s[98:99], s82, v138, 0
	v_lshl_add_u64 v[130:131], v[130:131], 1, s[84:85]
	v_lshl_add_u64 v[130:131], v[130:131], 0, s[38:39]
	v_lshl_add_u64 v[130:131], v[130:131], 0, v[128:129]
	global_load_dwordx4 v[206:209], v[130:131], off
	global_load_dwordx4 v[212:215], v[130:131], off offset:256
	v_add_u32_e32 v138, 0x20, v164
	v_mov_b64_e32 v[132:133], s[78:79]
	v_mad_i64_i32 v[132:133], s[98:99], v138, s50, v[132:133]
	v_lshl_add_u64 v[132:133], v[132:133], 0, s[38:39]
	v_lshl_add_u64 v[132:133], v[132:133], 0, v[128:129]
	global_load_dwordx4 v[216:219], v[132:133], off
	global_load_dwordx4 v[220:223], v[132:133], off offset:256
	v_mad_i64_i32 v[130:131], s[98:99], s82, v138, 0
	v_lshl_add_u64 v[130:131], v[130:131], 1, s[84:85]
	v_lshl_add_u64 v[130:131], v[130:131], 0, s[38:39]
	v_lshl_add_u64 v[130:131], v[130:131], 0, v[128:129]
	global_load_dwordx4 v[224:227], v[130:131], off
	global_load_dwordx4 v[228:231], v[130:131], off offset:256
	s_waitcnt vmcnt(8)
	v_mov_b32_e32 v138, v164
	v_mad_i64_i32 v[130:131], s[98:99], s82, v138, 0
	v_lshl_add_u64 v[130:131], v[130:131], 1, s[84:85]
	v_lshl_add_u64 v[130:131], v[130:131], 0, s[38:39]
	v_lshl_add_u64 v[130:131], v[130:131], 0, v[128:129]
	v_lshlrev_b32_e32 v166, 16, v182
	v_and_b32_e32 v167, 0xffff0000, v182
	v_lshlrev_b32_e32 v168, 16, v183
	v_and_b32_e32 v169, 0xffff0000, v183
	v_lshlrev_b32_e32 v170, 16, v184
	v_and_b32_e32 v171, 0xffff0000, v184
	v_lshlrev_b32_e32 v172, 16, v185
	v_and_b32_e32 v173, 0xffff0000, v185
	v_pk_mul_f32 v[166:167], v[124:125], v[166:167]
	v_pk_mul_f32 v[168:169], v[126:127], v[168:169]
	v_pk_mul_f32 v[170:171], v[120:121], v[170:171]
	v_pk_mul_f32 v[172:173], v[122:123], v[172:173]
	v_lshlrev_b32_e32 v174, 16, v190
	v_and_b32_e32 v175, 0xffff0000, v190
	v_pk_add_f32 v[166:167], v[166:167], v[174:175]
	v_lshlrev_b32_e32 v178, 16, v191
	v_and_b32_e32 v179, 0xffff0000, v191
	v_pk_add_f32 v[168:169], v[168:169], v[178:179]
	v_lshlrev_b32_e32 v174, 16, v192
	v_and_b32_e32 v175, 0xffff0000, v192
	v_pk_add_f32 v[170:171], v[170:171], v[174:175]
	v_lshlrev_b32_e32 v178, 16, v193
	v_and_b32_e32 v179, 0xffff0000, v193
	v_pk_add_f32 v[172:173], v[172:173], v[178:179]
	v_cvt_pk_bf16_f32 v134, v166, v167
	v_cvt_pk_bf16_f32 v135, v168, v169
	v_cvt_pk_bf16_f32 v136, v170, v171
	v_cvt_pk_bf16_f32 v137, v172, v173
	global_store_dwordx4 v[130:131], v[134:137], off
	v_lshlrev_b32_e32 v166, 16, v186
	v_and_b32_e32 v167, 0xffff0000, v186
	v_lshlrev_b32_e32 v168, 16, v187
	v_and_b32_e32 v169, 0xffff0000, v187
	v_lshlrev_b32_e32 v170, 16, v188
	v_and_b32_e32 v171, 0xffff0000, v188
	v_lshlrev_b32_e32 v172, 16, v189
	v_and_b32_e32 v173, 0xffff0000, v189
	v_pk_mul_f32 v[166:167], v[108:109], v[166:167]
	v_pk_mul_f32 v[168:169], v[110:111], v[168:169]
	v_pk_mul_f32 v[170:171], v[104:105], v[170:171]
	v_pk_mul_f32 v[172:173], v[106:107], v[172:173]
	v_lshlrev_b32_e32 v174, 16, v194
	v_and_b32_e32 v175, 0xffff0000, v194
	v_pk_add_f32 v[166:167], v[166:167], v[174:175]
	v_lshlrev_b32_e32 v178, 16, v195
	v_and_b32_e32 v179, 0xffff0000, v195
	v_pk_add_f32 v[168:169], v[168:169], v[178:179]
	v_lshlrev_b32_e32 v174, 16, v196
	v_and_b32_e32 v175, 0xffff0000, v196
	v_pk_add_f32 v[170:171], v[170:171], v[174:175]
	v_lshlrev_b32_e32 v178, 16, v197
	v_and_b32_e32 v179, 0xffff0000, v197
	v_pk_add_f32 v[172:173], v[172:173], v[178:179]
	v_cvt_pk_bf16_f32 v232, v166, v167
	v_cvt_pk_bf16_f32 v233, v168, v169
	v_cvt_pk_bf16_f32 v234, v170, v171
	v_cvt_pk_bf16_f32 v235, v172, v173
	global_store_dwordx4 v[130:131], v[232:235], off offset:256
	v_add_u32_e32 v138, 0x30, v164
	v_mov_b64_e32 v[132:133], s[78:79]
	v_mad_i64_i32 v[132:133], s[98:99], v138, s50, v[132:133]
	v_lshl_add_u64 v[132:133], v[132:133], 0, s[38:39]
	v_lshl_add_u64 v[132:133], v[132:133], 0, v[128:129]
	global_load_dwordx4 v[182:185], v[132:133], off
	global_load_dwordx4 v[186:189], v[132:133], off offset:256
	v_mad_i64_i32 v[130:131], s[98:99], s82, v138, 0
	v_lshl_add_u64 v[130:131], v[130:131], 1, s[84:85]
	v_lshl_add_u64 v[130:131], v[130:131], 0, s[38:39]
	v_lshl_add_u64 v[130:131], v[130:131], 0, v[128:129]
	global_load_dwordx4 v[190:193], v[130:131], off
	global_load_dwordx4 v[194:197], v[130:131], off offset:256
	s_waitcnt vmcnt(10)
; __device__ __forceinline__ float bf_lo(unsigned w) { return __uint_as_float(w << 16); }
; __device__ __forceinline__ float bf_hi(unsigned w) { return __uint_as_float(w & 0xffff0000u); }
;     __device__ __forceinline__ void operator()(const f32x4 (&acc)[2][2][4][2], const Unit& u, int wr, int wc, int fr, int fq) const {
;     ...
;         } else {
; #pragma unroll
;             for (int ai = 0; ai < 2; ++ai)
; #pragma unroll
;                 for (int m = 0; m < 4; ++m) { const int row = row0 + ai * HALF + m * 16;
;                     bf16_t* rowp = O + (size_t)row * ldc + u.pn * BM + cw; const bf16_t* gp = gate + (size_t)row * ldg + u.pn * BM + cw;
; #pragma unroll
;                     for (int bj = 0; bj < 2; ++bj) { const u32x4 gw = *(const u32x4*)(gp + bj * HALF);
;                         f32x4 v0 = acc[ai][bj][m][0], v1 = acc[ai][bj][m][1];
;                         v0[0] *= bf_lo(gw.x); v0[1] *= bf_hi(gw.x); v0[2] *= bf_lo(gw.y); v0[3] *= bf_hi(gw.y);
;                         v1[0] *= bf_lo(gw.z); v1[1] *= bf_hi(gw.z); v1[2] *= bf_lo(gw.w); v1[3] *= bf_hi(gw.w);
;                         if (mode == M_NAOUT) { const u32x4 pw = *(const u32x4*)(rowp + bj * HALF);
;                             v0[0] += bf_lo(pw.x); v0[1] += bf_hi(pw.x); v0[2] += bf_lo(pw.y); v0[3] += bf_hi(pw.y);
;                             v1[0] += bf_lo(pw.z); v1[1] += bf_hi(pw.z); v1[2] += bf_lo(pw.w); v1[3] += bf_hi(pw.w); }
;                         store8(rowp + bj * HALF, v0, v1); } }
	v_add_u32_e32 v138, 0x10, v164
	v_mad_i64_i32 v[130:131], s[98:99], s82, v138, 0
	v_lshl_add_u64 v[130:131], v[130:131], 1, s[84:85]
	v_lshl_add_u64 v[130:131], v[130:131], 0, s[38:39]
	v_lshl_add_u64 v[130:131], v[130:131], 0, v[128:129]
	v_lshlrev_b32_e32 v166, 16, v198
	v_and_b32_e32 v167, 0xffff0000, v198
	v_lshlrev_b32_e32 v168, 16, v199
	v_and_b32_e32 v169, 0xffff0000, v199
	v_lshlrev_b32_e32 v170, 16, v200
	v_and_b32_e32 v171, 0xffff0000, v200
	v_lshlrev_b32_e32 v172, 16, v201
	v_and_b32_e32 v173, 0xffff0000, v201
	v_pk_mul_f32 v[166:167], v[116:117], v[166:167]
	v_pk_mul_f32 v[168:169], v[118:119], v[168:169]
	v_pk_mul_f32 v[170:171], v[112:113], v[170:171]
	v_pk_mul_f32 v[172:173], v[114:115], v[172:173]
	v_lshlrev_b32_e32 v174, 16, v206
	v_and_b32_e32 v175, 0xffff0000, v206
	v_pk_add_f32 v[166:167], v[166:167], v[174:175]
	v_lshlrev_b32_e32 v178, 16, v207
	v_and_b32_e32 v179, 0xffff0000, v207
	v_pk_add_f32 v[168:169], v[168:169], v[178:179]
	v_lshlrev_b32_e32 v174, 16, v208
	v_and_b32_e32 v175, 0xffff0000, v208
	v_pk_add_f32 v[170:171], v[170:171], v[174:175]
	v_lshlrev_b32_e32 v178, 16, v209
	v_and_b32_e32 v179, 0xffff0000, v209
	v_pk_add_f32 v[172:173], v[172:173], v[178:179]
	v_cvt_pk_bf16_f32 v134, v166, v167
	v_cvt_pk_bf16_f32 v135, v168, v169
	v_cvt_pk_bf16_f32 v136, v170, v171
	v_cvt_pk_bf16_f32 v137, v172, v173
	global_store_dwordx4 v[130:131], v[134:137], off
	v_lshlrev_b32_e32 v166, 16, v202
	v_and_b32_e32 v167, 0xffff0000, v202
	v_lshlrev_b32_e32 v168, 16, v203
	v_and_b32_e32 v169, 0xffff0000, v203
	v_lshlrev_b32_e32 v170, 16, v204
	v_and_b32_e32 v171, 0xffff0000, v204
	v_lshlrev_b32_e32 v172, 16, v205
	v_and_b32_e32 v173, 0xffff0000, v205
	v_pk_mul_f32 v[166:167], v[92:93], v[166:167]
	v_pk_mul_f32 v[168:169], v[94:95], v[168:169]
	v_pk_mul_f32 v[170:171], v[88:89], v[170:171]
	v_pk_mul_f32 v[172:173], v[90:91], v[172:173]
	v_lshlrev_b32_e32 v174, 16, v212
	v_and_b32_e32 v175, 0xffff0000, v212
	v_pk_add_f32 v[166:167], v[166:167], v[174:175]
	v_lshlrev_b32_e32 v178, 16, v213
	v_and_b32_e32 v179, 0xffff0000, v213
	v_pk_add_f32 v[168:169], v[168:169], v[178:179]
	v_lshlrev_b32_e32 v174, 16, v214
	v_and_b32_e32 v175, 0xffff0000, v214
	v_pk_add_f32 v[170:171], v[170:171], v[174:175]
	v_lshlrev_b32_e32 v178, 16, v215
	v_and_b32_e32 v179, 0xffff0000, v215
	v_pk_add_f32 v[172:173], v[172:173], v[178:179]
	v_cvt_pk_bf16_f32 v232, v166, v167
	v_cvt_pk_bf16_f32 v233, v168, v169
	v_cvt_pk_bf16_f32 v234, v170, v171
	v_cvt_pk_bf16_f32 v235, v172, v173
	global_store_dwordx4 v[130:131], v[232:235], off offset:256
	v_add_u32_e32 v138, 0x80, v164
	v_mov_b64_e32 v[132:133], s[78:79]
	v_mad_i64_i32 v[132:133], s[98:99], v138, s50, v[132:133]
	v_lshl_add_u64 v[132:133], v[132:133], 0, s[38:39]
	v_lshl_add_u64 v[132:133], v[132:133], 0, v[128:129]
	global_load_dwordx4 v[198:201], v[132:133], off
	global_load_dwordx4 v[202:205], v[132:133], off offset:256
	v_mad_i64_i32 v[130:131], s[98:99], s82, v138, 0
	v_lshl_add_u64 v[130:131], v[130:131], 1, s[84:85]
	v_lshl_add_u64 v[130:131], v[130:131], 0, s[38:39]
	v_lshl_add_u64 v[130:131], v[130:131], 0, v[128:129]
	global_load_dwordx4 v[206:209], v[130:131], off
	global_load_dwordx4 v[212:215], v[130:131], off offset:256
	s_waitcnt vmcnt(12)
	v_add_u32_e32 v138, 0x20, v164
	v_mad_i64_i32 v[130:131], s[98:99], s82, v138, 0
	v_lshl_add_u64 v[130:131], v[130:131], 1, s[84:85]
	v_lshl_add_u64 v[130:131], v[130:131], 0, s[38:39]
	v_lshl_add_u64 v[130:131], v[130:131], 0, v[128:129]
	v_lshlrev_b32_e32 v166, 16, v216
	v_and_b32_e32 v167, 0xffff0000, v216
	v_lshlrev_b32_e32 v168, 16, v217
	v_and_b32_e32 v169, 0xffff0000, v217
	v_lshlrev_b32_e32 v170, 16, v218
	v_and_b32_e32 v171, 0xffff0000, v218
	v_lshlrev_b32_e32 v172, 16, v219
	v_and_b32_e32 v173, 0xffff0000, v219
	v_pk_mul_f32 v[166:167], v[100:101], v[166:167]
	v_pk_mul_f32 v[168:169], v[102:103], v[168:169]
	v_pk_mul_f32 v[170:171], v[96:97], v[170:171]
	v_pk_mul_f32 v[172:173], v[98:99], v[172:173]
	v_lshlrev_b32_e32 v174, 16, v224
	v_and_b32_e32 v175, 0xffff0000, v224
	v_pk_add_f32 v[166:167], v[166:167], v[174:175]
	v_lshlrev_b32_e32 v178, 16, v225
	v_and_b32_e32 v179, 0xffff0000, v225
	v_pk_add_f32 v[168:169], v[168:169], v[178:179]
	v_lshlrev_b32_e32 v174, 16, v226
	v_and_b32_e32 v175, 0xffff0000, v226
	v_pk_add_f32 v[170:171], v[170:171], v[174:175]
	v_lshlrev_b32_e32 v178, 16, v227
	v_and_b32_e32 v179, 0xffff0000, v227
	v_pk_add_f32 v[172:173], v[172:173], v[178:179]
	v_cvt_pk_bf16_f32 v134, v166, v167
	v_cvt_pk_bf16_f32 v135, v168, v169
	v_cvt_pk_bf16_f32 v136, v170, v171
	v_cvt_pk_bf16_f32 v137, v172, v173
	global_store_dwordx4 v[130:131], v[134:137], off
	v_lshlrev_b32_e32 v166, 16, v220
	v_and_b32_e32 v167, 0xffff0000, v220
	v_lshlrev_b32_e32 v168, 16, v221
	v_and_b32_e32 v169, 0xffff0000, v221
	v_lshlrev_b32_e32 v170, 16, v222
	v_and_b32_e32 v171, 0xffff0000, v222
	v_lshlrev_b32_e32 v172, 16, v223
	v_and_b32_e32 v173, 0xffff0000, v223
	v_pk_mul_f32 v[166:167], v[76:77], v[166:167]
	v_pk_mul_f32 v[168:169], v[78:79], v[168:169]
	v_pk_mul_f32 v[170:171], v[72:73], v[170:171]
	v_pk_mul_f32 v[172:173], v[74:75], v[172:173]
	v_lshlrev_b32_e32 v174, 16, v228
	v_and_b32_e32 v175, 0xffff0000, v228
	v_pk_add_f32 v[166:167], v[166:167], v[174:175]
	v_lshlrev_b32_e32 v178, 16, v229
	v_and_b32_e32 v179, 0xffff0000, v229
	v_pk_add_f32 v[168:169], v[168:169], v[178:179]
	v_lshlrev_b32_e32 v174, 16, v230
	v_and_b32_e32 v175, 0xffff0000, v230
	v_pk_add_f32 v[170:171], v[170:171], v[174:175]
	v_lshlrev_b32_e32 v178, 16, v231
	v_and_b32_e32 v179, 0xffff0000, v231
	v_pk_add_f32 v[172:173], v[172:173], v[178:179]
	v_cvt_pk_bf16_f32 v232, v166, v167
	v_cvt_pk_bf16_f32 v233, v168, v169
	v_cvt_pk_bf16_f32 v234, v170, v171
	v_cvt_pk_bf16_f32 v235, v172, v173
	global_store_dwordx4 v[130:131], v[232:235], off offset:256
	v_add_u32_e32 v138, 0x90, v164
	v_mov_b64_e32 v[132:133], s[78:79]
	v_mad_i64_i32 v[132:133], s[98:99], v138, s50, v[132:133]
	v_lshl_add_u64 v[132:133], v[132:133], 0, s[38:39]
	v_lshl_add_u64 v[132:133], v[132:133], 0, v[128:129]
	global_load_dwordx4 v[216:219], v[132:133], off
	global_load_dwordx4 v[220:223], v[132:133], off offset:256
	v_mad_i64_i32 v[130:131], s[98:99], s82, v138, 0
	v_lshl_add_u64 v[130:131], v[130:131], 1, s[84:85]
	v_lshl_add_u64 v[130:131], v[130:131], 0, s[38:39]
	v_lshl_add_u64 v[130:131], v[130:131], 0, v[128:129]
	global_load_dwordx4 v[224:227], v[130:131], off
	global_load_dwordx4 v[228:231], v[130:131], off offset:256
	s_waitcnt vmcnt(12)
; __device__ __forceinline__ float bf_lo(unsigned w) { return __uint_as_float(w << 16); }
; __device__ __forceinline__ float bf_hi(unsigned w) { return __uint_as_float(w & 0xffff0000u); }
;     __device__ __forceinline__ void operator()(const f32x4 (&acc)[2][2][4][2], const Unit& u, int wr, int wc, int fr, int fq) const {
;     ...
;         } else {
; #pragma unroll
;             for (int ai = 0; ai < 2; ++ai)
; #pragma unroll
;                 for (int m = 0; m < 4; ++m) { const int row = row0 + ai * HALF + m * 16;
;                     bf16_t* rowp = O + (size_t)row * ldc + u.pn * BM + cw; const bf16_t* gp = gate + (size_t)row * ldg + u.pn * BM + cw;
; #pragma unroll
;                     for (int bj = 0; bj < 2; ++bj) { const u32x4 gw = *(const u32x4*)(gp + bj * HALF);
;                         f32x4 v0 = acc[ai][bj][m][0], v1 = acc[ai][bj][m][1];
;                         v0[0] *= bf_lo(gw.x); v0[1] *= bf_hi(gw.x); v0[2] *= bf_lo(gw.y); v0[3] *= bf_hi(gw.y);
;                         v1[0] *= bf_lo(gw.z); v1[1] *= bf_hi(gw.z); v1[2] *= bf_lo(gw.w); v1[3] *= bf_hi(gw.w);
;                         if (mode == M_NAOUT) { const u32x4 pw = *(const u32x4*)(rowp + bj * HALF);
;                             v0[0] += bf_lo(pw.x); v0[1] += bf_hi(pw.x); v0[2] += bf_lo(pw.y); v0[3] += bf_hi(pw.y);
;                             v1[0] += bf_lo(pw.z); v1[1] += bf_hi(pw.z); v1[2] += bf_lo(pw.w); v1[3] += bf_hi(pw.w); }
;                         store8(rowp + bj * HALF, v0, v1); } }
	v_add_u32_e32 v138, 0x30, v164
	v_mad_i64_i32 v[130:131], s[98:99], s82, v138, 0
	v_lshl_add_u64 v[130:131], v[130:131], 1, s[84:85]
	v_lshl_add_u64 v[130:131], v[130:131], 0, s[38:39]
	v_lshl_add_u64 v[130:131], v[130:131], 0, v[128:129]
	v_lshlrev_b32_e32 v166, 16, v182
	v_and_b32_e32 v167, 0xffff0000, v182
	v_lshlrev_b32_e32 v168, 16, v183
	v_and_b32_e32 v169, 0xffff0000, v183
	v_lshlrev_b32_e32 v170, 16, v184
	v_and_b32_e32 v171, 0xffff0000, v184
	v_lshlrev_b32_e32 v172, 16, v185
	v_and_b32_e32 v173, 0xffff0000, v185
	v_pk_mul_f32 v[166:167], v[84:85], v[166:167]
	v_pk_mul_f32 v[168:169], v[86:87], v[168:169]
	v_pk_mul_f32 v[170:171], v[80:81], v[170:171]
	v_pk_mul_f32 v[172:173], v[82:83], v[172:173]
	v_lshlrev_b32_e32 v174, 16, v190
	v_and_b32_e32 v175, 0xffff0000, v190
	v_pk_add_f32 v[166:167], v[166:167], v[174:175]
	v_lshlrev_b32_e32 v178, 16, v191
	v_and_b32_e32 v179, 0xffff0000, v191
	v_pk_add_f32 v[168:169], v[168:169], v[178:179]
	v_lshlrev_b32_e32 v174, 16, v192
	v_and_b32_e32 v175, 0xffff0000, v192
	v_pk_add_f32 v[170:171], v[170:171], v[174:175]
	v_lshlrev_b32_e32 v178, 16, v193
	v_and_b32_e32 v179, 0xffff0000, v193
	v_pk_add_f32 v[172:173], v[172:173], v[178:179]
	v_cvt_pk_bf16_f32 v134, v166, v167
	v_cvt_pk_bf16_f32 v135, v168, v169
	v_cvt_pk_bf16_f32 v136, v170, v171
	v_cvt_pk_bf16_f32 v137, v172, v173
	global_store_dwordx4 v[130:131], v[134:137], off
	v_lshlrev_b32_e32 v166, 16, v186
	v_and_b32_e32 v167, 0xffff0000, v186
	v_lshlrev_b32_e32 v168, 16, v187
	v_and_b32_e32 v169, 0xffff0000, v187
	v_lshlrev_b32_e32 v170, 16, v188
	v_and_b32_e32 v171, 0xffff0000, v188
	v_lshlrev_b32_e32 v172, 16, v189
	v_and_b32_e32 v173, 0xffff0000, v189
	v_pk_mul_f32 v[166:167], v[68:69], v[166:167]
	v_pk_mul_f32 v[168:169], v[70:71], v[168:169]
	v_pk_mul_f32 v[170:171], v[64:65], v[170:171]
	v_pk_mul_f32 v[172:173], v[66:67], v[172:173]
	v_lshlrev_b32_e32 v174, 16, v194
	v_and_b32_e32 v175, 0xffff0000, v194
	v_pk_add_f32 v[166:167], v[166:167], v[174:175]
	v_lshlrev_b32_e32 v178, 16, v195
	v_and_b32_e32 v179, 0xffff0000, v195
	v_pk_add_f32 v[168:169], v[168:169], v[178:179]
	v_lshlrev_b32_e32 v174, 16, v196
	v_and_b32_e32 v175, 0xffff0000, v196
	v_pk_add_f32 v[170:171], v[170:171], v[174:175]
	v_lshlrev_b32_e32 v178, 16, v197
	v_and_b32_e32 v179, 0xffff0000, v197
	v_pk_add_f32 v[172:173], v[172:173], v[178:179]
	v_cvt_pk_bf16_f32 v232, v166, v167
	v_cvt_pk_bf16_f32 v233, v168, v169
	v_cvt_pk_bf16_f32 v234, v170, v171
	v_cvt_pk_bf16_f32 v235, v172, v173
	global_store_dwordx4 v[130:131], v[232:235], off offset:256
	v_add_u32_e32 v138, 0xa0, v164
	v_mov_b64_e32 v[132:133], s[78:79]
	v_mad_i64_i32 v[132:133], s[98:99], v138, s50, v[132:133]
	v_lshl_add_u64 v[132:133], v[132:133], 0, s[38:39]
	v_lshl_add_u64 v[132:133], v[132:133], 0, v[128:129]
	global_load_dwordx4 v[182:185], v[132:133], off
	global_load_dwordx4 v[186:189], v[132:133], off offset:256
	v_mad_i64_i32 v[130:131], s[98:99], s82, v138, 0
	v_lshl_add_u64 v[130:131], v[130:131], 1, s[84:85]
	v_lshl_add_u64 v[130:131], v[130:131], 0, s[38:39]
	v_lshl_add_u64 v[130:131], v[130:131], 0, v[128:129]
	global_load_dwordx4 v[190:193], v[130:131], off
	global_load_dwordx4 v[194:197], v[130:131], off offset:256
	s_waitcnt vmcnt(12)
	v_add_u32_e32 v138, 0x80, v164
	v_mad_i64_i32 v[130:131], s[98:99], s82, v138, 0
	v_lshl_add_u64 v[130:131], v[130:131], 1, s[84:85]
	v_lshl_add_u64 v[130:131], v[130:131], 0, s[38:39]
	v_lshl_add_u64 v[130:131], v[130:131], 0, v[128:129]
	v_lshlrev_b32_e32 v166, 16, v198
	v_and_b32_e32 v167, 0xffff0000, v198
	v_lshlrev_b32_e32 v168, 16, v199
	v_and_b32_e32 v169, 0xffff0000, v199
	v_lshlrev_b32_e32 v170, 16, v200
	v_and_b32_e32 v171, 0xffff0000, v200
	v_lshlrev_b32_e32 v172, 16, v201
	v_and_b32_e32 v173, 0xffff0000, v201
	v_pk_mul_f32 v[166:167], v[60:61], v[166:167]
	v_pk_mul_f32 v[168:169], v[62:63], v[168:169]
	v_pk_mul_f32 v[170:171], v[56:57], v[170:171]
	v_pk_mul_f32 v[172:173], v[58:59], v[172:173]
	v_lshlrev_b32_e32 v174, 16, v206
	v_and_b32_e32 v175, 0xffff0000, v206
	v_pk_add_f32 v[166:167], v[166:167], v[174:175]
	v_lshlrev_b32_e32 v178, 16, v207
	v_and_b32_e32 v179, 0xffff0000, v207
	v_pk_add_f32 v[168:169], v[168:169], v[178:179]
	v_lshlrev_b32_e32 v174, 16, v208
	v_and_b32_e32 v175, 0xffff0000, v208
	v_pk_add_f32 v[170:171], v[170:171], v[174:175]
	v_lshlrev_b32_e32 v178, 16, v209
	v_and_b32_e32 v179, 0xffff0000, v209
	v_pk_add_f32 v[172:173], v[172:173], v[178:179]
	v_cvt_pk_bf16_f32 v134, v166, v167
	v_cvt_pk_bf16_f32 v135, v168, v169
	v_cvt_pk_bf16_f32 v136, v170, v171
	v_cvt_pk_bf16_f32 v137, v172, v173
	global_store_dwordx4 v[130:131], v[134:137], off
	v_lshlrev_b32_e32 v166, 16, v202
	v_and_b32_e32 v167, 0xffff0000, v202
	v_lshlrev_b32_e32 v168, 16, v203
	v_and_b32_e32 v169, 0xffff0000, v203
	v_lshlrev_b32_e32 v170, 16, v204
	v_and_b32_e32 v171, 0xffff0000, v204
	v_lshlrev_b32_e32 v172, 16, v205
	v_and_b32_e32 v173, 0xffff0000, v205
	v_pk_mul_f32 v[166:167], v[44:45], v[166:167]
	v_pk_mul_f32 v[168:169], v[46:47], v[168:169]
	v_pk_mul_f32 v[170:171], v[40:41], v[170:171]
	v_pk_mul_f32 v[172:173], v[42:43], v[172:173]
	v_lshlrev_b32_e32 v174, 16, v212
	v_and_b32_e32 v175, 0xffff0000, v212
	v_pk_add_f32 v[166:167], v[166:167], v[174:175]
	v_lshlrev_b32_e32 v178, 16, v213
	v_and_b32_e32 v179, 0xffff0000, v213
	v_pk_add_f32 v[168:169], v[168:169], v[178:179]
	v_lshlrev_b32_e32 v174, 16, v214
	v_and_b32_e32 v175, 0xffff0000, v214
	v_pk_add_f32 v[170:171], v[170:171], v[174:175]
	v_lshlrev_b32_e32 v178, 16, v215
	v_and_b32_e32 v179, 0xffff0000, v215
	v_pk_add_f32 v[172:173], v[172:173], v[178:179]
	v_cvt_pk_bf16_f32 v232, v166, v167
	v_cvt_pk_bf16_f32 v233, v168, v169
	v_cvt_pk_bf16_f32 v234, v170, v171
	v_cvt_pk_bf16_f32 v235, v172, v173
	global_store_dwordx4 v[130:131], v[232:235], off offset:256
	v_add_u32_e32 v138, 0xb0, v164
	v_mov_b64_e32 v[132:133], s[78:79]
	v_mad_i64_i32 v[132:133], s[98:99], v138, s50, v[132:133]
	v_lshl_add_u64 v[132:133], v[132:133], 0, s[38:39]
	v_lshl_add_u64 v[132:133], v[132:133], 0, v[128:129]
	global_load_dwordx4 v[198:201], v[132:133], off
	global_load_dwordx4 v[202:205], v[132:133], off offset:256
	v_mad_i64_i32 v[130:131], s[98:99], s82, v138, 0
	v_lshl_add_u64 v[130:131], v[130:131], 1, s[84:85]
	v_lshl_add_u64 v[130:131], v[130:131], 0, s[38:39]
	v_lshl_add_u64 v[130:131], v[130:131], 0, v[128:129]
	global_load_dwordx4 v[206:209], v[130:131], off
	global_load_dwordx4 v[212:215], v[130:131], off offset:256
	s_waitcnt vmcnt(12)
; __device__ __forceinline__ float bf_lo(unsigned w) { return __uint_as_float(w << 16); }
; __device__ __forceinline__ float bf_hi(unsigned w) { return __uint_as_float(w & 0xffff0000u); }
;     __device__ __forceinline__ void operator()(const f32x4 (&acc)[2][2][4][2], const Unit& u, int wr, int wc, int fr, int fq) const {
;     ...
;         } else {
; #pragma unroll
;             for (int ai = 0; ai < 2; ++ai)
; #pragma unroll
;                 for (int m = 0; m < 4; ++m) { const int row = row0 + ai * HALF + m * 16;
;                     bf16_t* rowp = O + (size_t)row * ldc + u.pn * BM + cw; const bf16_t* gp = gate + (size_t)row * ldg + u.pn * BM + cw;
; #pragma unroll
;                     for (int bj = 0; bj < 2; ++bj) { const u32x4 gw = *(const u32x4*)(gp + bj * HALF);
;                         f32x4 v0 = acc[ai][bj][m][0], v1 = acc[ai][bj][m][1];
;                         v0[0] *= bf_lo(gw.x); v0[1] *= bf_hi(gw.x); v0[2] *= bf_lo(gw.y); v0[3] *= bf_hi(gw.y);
;                         v1[0] *= bf_lo(gw.z); v1[1] *= bf_hi(gw.z); v1[2] *= bf_lo(gw.w); v1[3] *= bf_hi(gw.w);
;                         if (mode == M_NAOUT) { const u32x4 pw = *(const u32x4*)(rowp + bj * HALF);
;                             v0[0] += bf_lo(pw.x); v0[1] += bf_hi(pw.x); v0[2] += bf_lo(pw.y); v0[3] += bf_hi(pw.y);
;                             v1[0] += bf_lo(pw.z); v1[1] += bf_hi(pw.z); v1[2] += bf_lo(pw.w); v1[3] += bf_hi(pw.w); }
;                         store8(rowp + bj * HALF, v0, v1); } }
	v_add_u32_e32 v138, 0x90, v164
	v_mad_i64_i32 v[130:131], s[98:99], s82, v138, 0
	v_lshl_add_u64 v[130:131], v[130:131], 1, s[84:85]
	v_lshl_add_u64 v[130:131], v[130:131], 0, s[38:39]
	v_lshl_add_u64 v[130:131], v[130:131], 0, v[128:129]
	v_lshlrev_b32_e32 v166, 16, v216
	v_and_b32_e32 v167, 0xffff0000, v216
	v_lshlrev_b32_e32 v168, 16, v217
	v_and_b32_e32 v169, 0xffff0000, v217
	v_lshlrev_b32_e32 v170, 16, v218
	v_and_b32_e32 v171, 0xffff0000, v218
	v_lshlrev_b32_e32 v172, 16, v219
	v_and_b32_e32 v173, 0xffff0000, v219
	v_pk_mul_f32 v[166:167], v[52:53], v[166:167]
	v_pk_mul_f32 v[168:169], v[54:55], v[168:169]
	v_pk_mul_f32 v[170:171], v[48:49], v[170:171]
	v_pk_mul_f32 v[172:173], v[50:51], v[172:173]
	v_lshlrev_b32_e32 v174, 16, v224
	v_and_b32_e32 v175, 0xffff0000, v224
	v_pk_add_f32 v[166:167], v[166:167], v[174:175]
	v_lshlrev_b32_e32 v178, 16, v225
	v_and_b32_e32 v179, 0xffff0000, v225
	v_pk_add_f32 v[168:169], v[168:169], v[178:179]
	v_lshlrev_b32_e32 v174, 16, v226
	v_and_b32_e32 v175, 0xffff0000, v226
	v_pk_add_f32 v[170:171], v[170:171], v[174:175]
	v_lshlrev_b32_e32 v178, 16, v227
	v_and_b32_e32 v179, 0xffff0000, v227
	v_pk_add_f32 v[172:173], v[172:173], v[178:179]
	v_cvt_pk_bf16_f32 v134, v166, v167
	v_cvt_pk_bf16_f32 v135, v168, v169
	v_cvt_pk_bf16_f32 v136, v170, v171
	v_cvt_pk_bf16_f32 v137, v172, v173
	global_store_dwordx4 v[130:131], v[134:137], off
	v_lshlrev_b32_e32 v166, 16, v220
	v_and_b32_e32 v167, 0xffff0000, v220
	v_lshlrev_b32_e32 v168, 16, v221
	v_and_b32_e32 v169, 0xffff0000, v221
	v_lshlrev_b32_e32 v170, 16, v222
	v_and_b32_e32 v171, 0xffff0000, v222
	v_lshlrev_b32_e32 v172, 16, v223
	v_and_b32_e32 v173, 0xffff0000, v223
	v_pk_mul_f32 v[166:167], v[28:29], v[166:167]
	v_pk_mul_f32 v[168:169], v[30:31], v[168:169]
	v_pk_mul_f32 v[170:171], v[24:25], v[170:171]
	v_pk_mul_f32 v[172:173], v[26:27], v[172:173]
	v_lshlrev_b32_e32 v174, 16, v228
	v_and_b32_e32 v175, 0xffff0000, v228
	v_pk_add_f32 v[166:167], v[166:167], v[174:175]
	v_lshlrev_b32_e32 v178, 16, v229
	v_and_b32_e32 v179, 0xffff0000, v229
	v_pk_add_f32 v[168:169], v[168:169], v[178:179]
	v_lshlrev_b32_e32 v174, 16, v230
	v_and_b32_e32 v175, 0xffff0000, v230
	v_pk_add_f32 v[170:171], v[170:171], v[174:175]
	v_lshlrev_b32_e32 v178, 16, v231
	v_and_b32_e32 v179, 0xffff0000, v231
	v_pk_add_f32 v[172:173], v[172:173], v[178:179]
	v_cvt_pk_bf16_f32 v232, v166, v167
	v_cvt_pk_bf16_f32 v233, v168, v169
	v_cvt_pk_bf16_f32 v234, v170, v171
	v_cvt_pk_bf16_f32 v235, v172, v173
	global_store_dwordx4 v[130:131], v[232:235], off offset:256
	s_waitcnt vmcnt(8)
	v_add_u32_e32 v138, 0xa0, v164
	v_mad_i64_i32 v[130:131], s[98:99], s82, v138, 0
	v_lshl_add_u64 v[130:131], v[130:131], 1, s[84:85]
	v_lshl_add_u64 v[130:131], v[130:131], 0, s[38:39]
	v_lshl_add_u64 v[130:131], v[130:131], 0, v[128:129]
	v_lshlrev_b32_e32 v166, 16, v182
	v_and_b32_e32 v167, 0xffff0000, v182
	v_lshlrev_b32_e32 v168, 16, v183
	v_and_b32_e32 v169, 0xffff0000, v183
	v_lshlrev_b32_e32 v170, 16, v184
	v_and_b32_e32 v171, 0xffff0000, v184
	v_lshlrev_b32_e32 v172, 16, v185
	v_and_b32_e32 v173, 0xffff0000, v185
	v_pk_mul_f32 v[166:167], v[36:37], v[166:167]
	v_pk_mul_f32 v[168:169], v[38:39], v[168:169]
	v_pk_mul_f32 v[170:171], v[32:33], v[170:171]
	v_pk_mul_f32 v[172:173], v[34:35], v[172:173]
	v_lshlrev_b32_e32 v174, 16, v190
	v_and_b32_e32 v175, 0xffff0000, v190
	v_pk_add_f32 v[166:167], v[166:167], v[174:175]
	v_lshlrev_b32_e32 v178, 16, v191
	v_and_b32_e32 v179, 0xffff0000, v191
	v_pk_add_f32 v[168:169], v[168:169], v[178:179]
	v_lshlrev_b32_e32 v174, 16, v192
	v_and_b32_e32 v175, 0xffff0000, v192
	v_pk_add_f32 v[170:171], v[170:171], v[174:175]
	v_lshlrev_b32_e32 v178, 16, v193
	v_and_b32_e32 v179, 0xffff0000, v193
	v_pk_add_f32 v[172:173], v[172:173], v[178:179]
	v_cvt_pk_bf16_f32 v134, v166, v167
	v_cvt_pk_bf16_f32 v135, v168, v169
	v_cvt_pk_bf16_f32 v136, v170, v171
	v_cvt_pk_bf16_f32 v137, v172, v173
	global_store_dwordx4 v[130:131], v[134:137], off
	v_lshlrev_b32_e32 v166, 16, v186
	v_and_b32_e32 v167, 0xffff0000, v186
	v_lshlrev_b32_e32 v168, 16, v187
	v_and_b32_e32 v169, 0xffff0000, v187
	v_lshlrev_b32_e32 v170, 16, v188
	v_and_b32_e32 v171, 0xffff0000, v188
	v_lshlrev_b32_e32 v172, 16, v189
	v_and_b32_e32 v173, 0xffff0000, v189
	v_pk_mul_f32 v[166:167], v[12:13], v[166:167]
	v_pk_mul_f32 v[168:169], v[14:15], v[168:169]
	v_pk_mul_f32 v[170:171], v[8:9], v[170:171]
	v_pk_mul_f32 v[172:173], v[10:11], v[172:173]
	v_lshlrev_b32_e32 v174, 16, v194
	v_and_b32_e32 v175, 0xffff0000, v194
	v_pk_add_f32 v[166:167], v[166:167], v[174:175]
	v_lshlrev_b32_e32 v178, 16, v195
	v_and_b32_e32 v179, 0xffff0000, v195
	v_pk_add_f32 v[168:169], v[168:169], v[178:179]
	v_lshlrev_b32_e32 v174, 16, v196
	v_and_b32_e32 v175, 0xffff0000, v196
	v_pk_add_f32 v[170:171], v[170:171], v[174:175]
	v_lshlrev_b32_e32 v178, 16, v197
	v_and_b32_e32 v179, 0xffff0000, v197
	v_pk_add_f32 v[172:173], v[172:173], v[178:179]
	v_cvt_pk_bf16_f32 v232, v166, v167
	v_cvt_pk_bf16_f32 v233, v168, v169
	v_cvt_pk_bf16_f32 v234, v170, v171
	v_cvt_pk_bf16_f32 v235, v172, v173
	global_store_dwordx4 v[130:131], v[232:235], off offset:256
	s_waitcnt vmcnt(4)
;     __device__ __forceinline__ void operator()(const f32x4 (&acc)[2][2][4][2], const Unit& u, int wr, int wc, int fr, int fq) const {
;     ...
;             f32x4 cv[2][2];
; #pragma unroll
;             for (int bj = 0; bj < 2; ++bj)
; #pragma unroll
;                 for (int n = 0; n < 2; ++n) { const f32x4 sv = *(const f32x4*)(rs + u.pn * BM + bj * HALF + cw + 4 * n);
; #pragma unroll
;                     for (int e = 0; e < 4; ++e) cv[bj][n][e] = __builtin_amdgcn_rsqf(sv[e] * (1.0f / 1024.0f) + 1e-6f); }
; #pragma unroll
;             for (int ai = 0; ai < 2; ++ai)
; #pragma unroll
;                 for (int m = 0; m < 4; ++m) { bf16_t* rowp = O + (size_t)(row0 + ai * HALF + m * 16) * ldc + u.pn * BM + cw;
; #pragma unroll
;                     for (int bj = 0; bj < 2; ++bj) {
;                         if (u.pm < 4) {
;                             const f32x4 v0 = acc[ai][bj][m][0] * cv[bj][0], v1 = acc[ai][bj][m][1] * cv[bj][1];
;                             bf16_t* gb = rowp + bj * HALF - 8 * (fq & 1) + 4 * (fq & 1);
;                             u32x2 w0, w1; w0.x = cvtpk(v0[0], v0[1]); w0.y = cvtpk(v0[2], v0[3]); w1.x = cvtpk(v1[0], v1[1]); w1.y = cvtpk(v1[2], v1[3]);
;     ...
; #pragma unroll
;             for (int ai = 0; ai < 2; ++ai)
; #pragma unroll
;                 for (int m = 0; m < 4; ++m) { const int row = row0 + ai * HALF + m * 16;
;                     bf16_t* rowp = O + (size_t)row * ldc + u.pn * BM + cw; const bf16_t* gp = gate + (size_t)row * ldg + u.pn * BM + cw;
; #pragma unroll
;                     for (int bj = 0; bj < 2; ++bj) { const u32x4 gw = *(const u32x4*)(gp + bj * HALF);
;                         f32x4 v0 = acc[ai][bj][m][0], v1 = acc[ai][bj][m][1];
;                         v0[0] *= bf_lo(gw.x); v0[1] *= bf_hi(gw.x); v0[2] *= bf_lo(gw.y); v0[3] *= bf_hi(gw.y);
;                         v1[0] *= bf_lo(gw.z); v1[1] *= bf_hi(gw.z); v1[2] *= bf_lo(gw.w); v1[3] *= bf_hi(gw.w);
;                         if (mode == M_NAOUT) { const u32x4 pw = *(const u32x4*)(rowp + bj * HALF);
;                             v0[0] += bf_lo(pw.x); v0[1] += bf_hi(pw.x); v0[2] += bf_lo(pw.y); v0[3] += bf_hi(pw.y);
;                             v1[0] += bf_lo(pw.z); v1[1] += bf_hi(pw.z); v1[2] += bf_lo(pw.w); v1[3] += bf_hi(pw.w); }
;                         store8(rowp + bj * HALF, v0, v1); } }
	v_add_u32_e32 v138, 0xb0, v164
	v_mad_i64_i32 v[130:131], s[98:99], s82, v138, 0
	v_lshl_add_u64 v[130:131], v[130:131], 1, s[84:85]
	v_lshl_add_u64 v[130:131], v[130:131], 0, s[38:39]
	v_lshl_add_u64 v[130:131], v[130:131], 0, v[128:129]
	v_lshlrev_b32_e32 v166, 16, v198
	v_and_b32_e32 v167, 0xffff0000, v198
	v_lshlrev_b32_e32 v168, 16, v199
	v_and_b32_e32 v169, 0xffff0000, v199
	v_lshlrev_b32_e32 v170, 16, v200
	v_and_b32_e32 v171, 0xffff0000, v200
	v_lshlrev_b32_e32 v172, 16, v201
	v_and_b32_e32 v173, 0xffff0000, v201
	v_pk_mul_f32 v[166:167], v[20:21], v[166:167]
	v_pk_mul_f32 v[168:169], v[22:23], v[168:169]
	v_pk_mul_f32 v[170:171], v[16:17], v[170:171]
	v_pk_mul_f32 v[172:173], v[18:19], v[172:173]
	v_lshlrev_b32_e32 v174, 16, v206
	v_and_b32_e32 v175, 0xffff0000, v206
	v_pk_add_f32 v[166:167], v[166:167], v[174:175]
	v_lshlrev_b32_e32 v178, 16, v207
	v_and_b32_e32 v179, 0xffff0000, v207
	v_pk_add_f32 v[168:169], v[168:169], v[178:179]
	v_lshlrev_b32_e32 v174, 16, v208
	v_and_b32_e32 v175, 0xffff0000, v208
	v_pk_add_f32 v[170:171], v[170:171], v[174:175]
	v_lshlrev_b32_e32 v178, 16, v209
	v_and_b32_e32 v179, 0xffff0000, v209
	v_pk_add_f32 v[172:173], v[172:173], v[178:179]
	v_cvt_pk_bf16_f32 v134, v166, v167
	v_cvt_pk_bf16_f32 v135, v168, v169
	v_cvt_pk_bf16_f32 v136, v170, v171
	v_cvt_pk_bf16_f32 v137, v172, v173
	global_store_dwordx4 v[130:131], v[134:137], off
	v_lshlrev_b32_e32 v166, 16, v202
	v_and_b32_e32 v167, 0xffff0000, v202
	v_lshlrev_b32_e32 v168, 16, v203
	v_and_b32_e32 v169, 0xffff0000, v203
	v_lshlrev_b32_e32 v170, 16, v204
	v_and_b32_e32 v171, 0xffff0000, v204
	v_lshlrev_b32_e32 v172, 16, v205
	v_and_b32_e32 v173, 0xffff0000, v205
	v_pk_mul_f32 v[166:167], v[4:5], v[166:167]
	v_pk_mul_f32 v[168:169], v[6:7], v[168:169]
	v_pk_mul_f32 v[170:171], v[0:1], v[170:171]
	v_pk_mul_f32 v[172:173], v[2:3], v[172:173]
	v_lshlrev_b32_e32 v174, 16, v212
	v_and_b32_e32 v175, 0xffff0000, v212
	v_pk_add_f32 v[166:167], v[166:167], v[174:175]
	v_lshlrev_b32_e32 v178, 16, v213
	v_and_b32_e32 v179, 0xffff0000, v213
	v_pk_add_f32 v[168:169], v[168:169], v[178:179]
	v_lshlrev_b32_e32 v174, 16, v214
	v_and_b32_e32 v175, 0xffff0000, v214
	v_pk_add_f32 v[170:171], v[170:171], v[174:175]
	v_lshlrev_b32_e32 v178, 16, v215
	v_and_b32_e32 v179, 0xffff0000, v215
	v_pk_add_f32 v[172:173], v[172:173], v[178:179]
	v_cvt_pk_bf16_f32 v232, v166, v167
	v_cvt_pk_bf16_f32 v233, v168, v169
	v_cvt_pk_bf16_f32 v234, v170, v171
	v_cvt_pk_bf16_f32 v235, v172, v173
	global_store_dwordx4 v[130:131], v[232:235], off offset:256
.Lgate_done:
	s_mov_b64 s[6:7], 0
.LBB0_420:
	s_and_b64 vcc, exec, s[6:7]
	s_cbranch_vccz .LBB0_485
	s_lshl_b32 s38, s40, 8
	s_ashr_i32 s39, s38, 31
	v_lshl_add_u64 v[128:129], s[38:39], 2, v[154:155]
	flat_load_dwordx4 v[136:139], v[128:129]
	flat_load_dwordx4 v[166:169], v[128:129] offset:16
	flat_load_dwordx4 v[132:135], v[128:129] offset:512
	s_nop 0
	flat_load_dwordx4 v[128:131], v[128:129] offset:528
	v_mad_i64_i32 v[170:171], s[6:7], s82, v164, 0
	v_lshl_add_u64 v[170:171], v[170:171], 1, s[84:85]
	v_lshl_add_u64 v[170:171], s[38:39], 1, v[170:171]
	v_lshl_add_u64 v[174:175], v[148:149], 1, v[170:171]
	s_cmp_gt_i32 s48, 3
	s_cselect_b64 s[98:99], -1, 0
	s_mov_b64 s[6:7], -1
	s_and_b64 vcc, exec, s[98:99]
	s_waitcnt vmcnt(0) lgkmcnt(0)
	v_fmamk_f32 v136, v136, 0x3a800000, v237
	v_fmamk_f32 v137, v137, 0x3a800000, v237
	v_fmamk_f32 v138, v138, 0x3a800000, v237
	v_fmamk_f32 v139, v139, 0x3a800000, v237
	v_fmamk_f32 v165, v166, 0x3a800000, v237
	v_fmamk_f32 v167, v167, 0x3a800000, v237
	v_fmamk_f32 v168, v168, 0x3a800000, v237
	v_fmamk_f32 v169, v169, 0x3a800000, v237
	v_rsq_f32_e32 v170, v136
	v_rsq_f32_e32 v171, v137
	v_rsq_f32_e32 v172, v138
	v_rsq_f32_e32 v173, v139
	v_rsq_f32_e32 v166, v165
	v_rsq_f32_e32 v168, v168
	v_rsq_f32_e32 v169, v169
	v_rsq_f32_e32 v167, v167
	v_pk_mul_f32 v[138:139], v[126:127], v[172:173]
	v_pk_mul_f32 v[136:137], v[124:125], v[170:171]
	v_pk_mul_f32 v[178:179], v[122:123], v[168:169]
	v_pk_mul_f32 v[182:183], v[120:121], v[166:167]
	v_cvt_pk_bf16_f32 v136, v136, v137
	v_cvt_pk_bf16_f32 v137, v138, v139
	v_cvt_pk_bf16_f32 v138, v182, v183
	v_cvt_pk_bf16_f32 v139, v178, v179
	s_cbranch_vccz .LBB0_423
	flat_store_dwordx4 v[174:175], v[136:139]
	s_mov_b64 s[6:7], 0
